# K-loops for all tiles incl. half-width tile (waves 4-7 staging only); without the attention prologue change
# speedup vs baseline: 1.3966x; 1.0133x over previous
;     ...
;   const int lane = tid & 63, wave = __builtin_amdgcn_readfirstlane(tid >> 6), l31 = lane & 31, h = lane >> 5;
;   const int wr = partial ? ((wave & 3) >> 1) : (wave >> 2);
;   const int wc = partial ? ((wave & 1) + 2 * (wave >> 2)) : (wave & 3);
;   const bool domma = !partial || wave < 4;
;   u16* As0 = (u16*)lds;
;   u16* Bs0 = As0 + 2 * 256 * LD;
;   f32x16 acc[2][4];
; #pragma unroll
;   for (int a = 0; a < 2; ++a)
; #pragma unroll
;     for (int b = 0; b < 4; ++b)
; #pragma unroll
;       for (int r = 0; r < 16; ++r) acc[a][b][r] = 0.f;
;   u32x4 ra[4], rb[4];
;   const int srow = tid >> 3, skc = tid & 7;
;   const u16* Ag = A + (size_t)(m0 + srow) * K + skc * 8;
;   const u16* Bg[4];
; #pragma unroll
;   for (int i = 0; i < 4; ++i) { int n = n0 + srow + 64 * i; n = n < nmax ? n : nmax - 1; Bg[i] = Bt + (size_t)n * K + skc * 8; }
;   const int nk = nk_override ? nk_override : K / 64;
; #pragma unroll
;   for (int i = 0; i < 4; ++i) { ra[i] = *(const u32x4*)(Ag + (size_t)(64 * i) * K); rb[i] = *(const u32x4*)(Bg[i]); }
; #pragma unroll
;   for (int i = 0; i < 4; ++i) { *(u32x4*)(As0 + (srow + 64 * i) * LD + skc * 8) = ra[i]; *(u32x4*)(Bs0 + (srow + 64 * i) * LD + skc * 8) = rb[i]; }
;   if (nk > 1) {
; #pragma unroll
;     for (int i = 0; i < 4; ++i) { ra[i] = *(const u32x4*)(Ag + (size_t)(64 * i) * K + 64); rb[i] = *(const u32x4*)(Bg[i] + 64); }
;     ...
;   for (int Lx = jx; Lx < (NMT / 8) * NNT; Lx += nbx) {
;     const int grp = Lx / (2 * NNT), gi = Lx % (2 * NNT);
;     const int mt = xcd * (NMT / 8) + 2 * grp + (gi & 1), nt = gi >> 1;
.LBB0_107:
	s_lshl_b32 s34, s34, 1
	s_add_i32 s34, s34, s40
	s_and_b32 s30, s35, 1
	s_or_b32 s30, s34, s30
	s_lshl_b32 s59, s62, 8
	v_ashrrev_i32_e32 v42, 3, v227
	s_lshl_b32 s35, s30, 8
	s_waitcnt vmcnt(3)
	v_add_u32_e32 v10, s59, v42
	s_waitcnt vmcnt(0)
	v_add_u32_e32 v4, s35, v42
	v_lshlrev_b32_e32 v2, 4, v227
	v_min_i32_e32 v8, 0x107f, v10
	v_ashrrev_i32_e32 v5, 31, v4
	v_and_b32_e32 v2, 0x70, v2
	v_ashrrev_i32_e32 v9, 31, v8
	v_lshlrev_b64 v[4:5], 11, v[4:5]
	s_waitcnt lgkmcnt(0)
	v_lshl_add_u64 v[6:7], s[18:19], 0, v[2:3]
	v_lshlrev_b64 v[8:9], 11, v[8:9]
	v_lshl_add_u64 v[228:229], v[6:7], 0, v[8:9]
	v_min_i32_e32 v8, 0x103f, v10
	v_lshl_add_u64 v[4:5], s[16:17], 0, v[4:5]
	v_ashrrev_i32_e32 v9, 31, v8
	v_lshl_add_u64 v[230:231], v[4:5], 0, v[2:3]
	v_lshlrev_b64 v[8:9], 11, v[8:9]
	v_add_co_u32_e32 v232, vcc, s42, v230
	v_lshl_add_u64 v[36:37], v[6:7], 0, v[8:9]
	v_min_i32_e32 v8, 0xfff, v10
	v_addc_co_u32_e32 v233, vcc, 0, v231, vcc
	v_ashrrev_i32_e32 v9, 31, v8
	v_add_co_u32_e32 v16, vcc, s42, v36
	v_lshlrev_b64 v[8:9], 11, v[8:9]
	s_nop 0
	v_addc_co_u32_e32 v17, vcc, 0, v37, vcc
	v_lshl_add_u64 v[38:39], v[6:7], 0, v[8:9]
	v_min_i32_e32 v8, 0xfbf, v10
	v_add_co_u32_e32 v68, vcc, s43, v230
	v_ashrrev_i32_e32 v9, 31, v8
	s_nop 0
	v_addc_co_u32_e32 v69, vcc, 0, v231, vcc
	v_lshlrev_b64 v[8:9], 11, v[8:9]
	v_add_co_u32_e32 v24, vcc, s43, v38
	v_lshl_add_u64 v[40:41], v[6:7], 0, v[8:9]
	global_load_dwordx4 v[4:7], v[230:231], off
	global_load_dwordx4 v[8:11], v[228:229], off
	v_addc_co_u32_e32 v25, vcc, 0, v39, vcc
	global_load_dwordx4 v[16:19], v[16:17], off
	v_add_co_u32_e32 v28, vcc, s44, v40
	global_load_dwordx4 v[24:27], v[24:25], off
	s_nop 0
	v_addc_co_u32_e32 v29, vcc, 0, v41, vcc
	global_load_dwordx4 v[28:31], v[28:29], off
	v_add_co_u32_e32 v70, vcc, s44, v230
	global_load_dwordx4 v[12:15], v[232:233], off
	global_load_dwordx4 v[20:23], v[68:69], off
	v_addc_co_u32_e32 v71, vcc, 0, v231, vcc
	global_load_dwordx4 v[32:35], v[70:71], off
	v_mul_lo_u32 v42, v42, s46
	v_add3_u32 v251, s45, v2, v42
	v_add3_u32 v250, 0, v2, v42
	v_lshl_add_u64 v[238:239], v[36:37], 0, s[24:25]
	v_lshl_add_u64 v[234:235], v[38:39], 0, s[26:27]
	v_lshl_add_u64 v[236:237], v[40:41], 0, s[28:29]
	global_load_dwordx4 v[36:39], v[228:229], off offset:128
	global_load_dwordx4 v[40:43], v[238:239], off offset:128
	global_load_dwordx4 v[44:47], v[234:235], off offset:128
	global_load_dwordx4 v[48:51], v[236:237], off offset:128
	global_load_dwordx4 v[52:55], v[230:231], off offset:128
	global_load_dwordx4 v[56:59], v[232:233], off offset:128
	global_load_dwordx4 v[60:63], v[68:69], off offset:128
	global_load_dwordx4 v[64:67], v[70:71], off offset:128
	s_ashr_i32 s36, s60, 6
	s_bfe_u32 s37, s36, 0x10001
	s_ashr_i32 s38, s60, 8
	s_and_b64 s[30:31], s[6:7], exec
	s_cselect_b32 s37, s37, s38
	s_xor_b64 s[6:7], s[6:7], -1
	s_cmp_lt_i32 s36, 4
	v_and_b32_e32 v225, 31, v227
	s_cselect_b64 s[30:31], -1, 0
	s_lshl_b32 s36, s37, 7
	v_bfe_u32 v247, v227, 5, 1
	v_or_b32_e32 v2, s36, v225
	v_mul_lo_u32 v2, v2, s46
	v_lshlrev_b32_e32 v226, 4, v247
	s_lshl_b32 s61, s20, 6
	v_add3_u32 v248, 0, v2, v226
	v_or_b32_e32 v2, s61, v225
	v_mul_lo_u32 v2, v2, s46
	s_or_b64 s[30:31], s[6:7], s[30:31]
	v_add3_u32 v249, s45, v2, v226
	s_waitcnt vmcnt(14)
	ds_write_b128 v251, v[8:11]
	s_waitcnt vmcnt(13)
	ds_write_b128 v251, v[16:19] offset:9216
	s_waitcnt vmcnt(12)
	ds_write_b128 v251, v[24:27] offset:18432
	s_waitcnt vmcnt(11)
	ds_write_b128 v251, v[28:31] offset:27648
	ds_write_b128 v250, v[4:7]
	s_waitcnt vmcnt(10)
	ds_write_b128 v250, v[12:15] offset:9216
	s_waitcnt vmcnt(9)
	ds_write_b128 v250, v[20:23] offset:18432
	s_waitcnt vmcnt(8)
	ds_write_b128 v250, v[32:35] offset:27648
	s_waitcnt lgkmcnt(0)
	s_barrier
	s_andn2_b64 vcc, exec, s[30:31]
	s_cbranch_vccnz .Lp1_stage_only
	v_lshrrev_b32_e32 v227, 3, v223
	v_lshlrev_b32_e32 v227, 11, v227
	v_lshlrev_b32_e32 v2, 4, v223
	v_and_b32_e32 v2, 0x70, v2
	v_or_b32_e32 v227, v227, v2
	s_lshl_b32 s6, s35, 11
	s_add_u32 s74, s16, s6
	s_addc_u32 s75, s17, 0
	s_add_u32 s76, s74, 0x20000
	s_addc_u32 s77, s75, 0
	s_add_u32 s78, s74, 0x40000
	s_addc_u32 s79, s75, 0
	s_add_u32 s80, s74, 0x60000
	s_addc_u32 s81, s75, 0
	s_lshl_b32 s6, s59, 11
	s_add_u32 s82, s18, s6
	s_addc_u32 s83, s19, 0
	s_add_u32 s84, s82, 0x20000
	s_addc_u32 s85, s83, 0
	s_add_u32 s86, s82, 0x40000
	s_addc_u32 s87, s83, 0
	s_add_u32 s92, s82, 0x60000
	s_addc_u32 s93, s83, 0
	global_load_dwordx4 v[146:149], v227, s[74:75] offset:256
	global_load_dwordx4 v[178:181], v227, s[82:83] offset:256
	global_load_dwordx4 v[150:153], v227, s[76:77] offset:256
	global_load_dwordx4 v[182:185], v227, s[84:85] offset:256
	global_load_dwordx4 v[154:157], v227, s[78:79] offset:256
	global_load_dwordx4 v[186:189], v227, s[86:87] offset:256
	global_load_dwordx4 v[158:161], v227, s[80:81] offset:256
	global_load_dwordx4 v[190:193], v227, s[92:93] offset:256
	global_load_dwordx4 v[162:165], v227, s[74:75] offset:384
	global_load_dwordx4 v[194:197], v227, s[82:83] offset:384
	global_load_dwordx4 v[166:169], v227, s[76:77] offset:384
	global_load_dwordx4 v[198:201], v227, s[84:85] offset:384
	global_load_dwordx4 v[170:173], v227, s[78:79] offset:384
	global_load_dwordx4 v[202:205], v227, s[86:87] offset:384
	global_load_dwordx4 v[174:177], v227, s[80:81] offset:384
	global_load_dwordx4 v[206:209], v227, s[92:93] offset:384
	s_waitcnt vmcnt(23)
	ds_write_b128 v251, v[36:39] offset:36864
	s_waitcnt vmcnt(22)
	ds_write_b128 v251, v[40:43] offset:46080
	s_waitcnt vmcnt(21)
	ds_write_b128 v251, v[44:47] offset:55296
	s_waitcnt vmcnt(20)
	ds_write_b128 v251, v[48:51] offset:64512
	s_waitcnt vmcnt(19)
;     ...
; #pragma unroll
;   for (int i = 0; i < 4; ++i) { ra[i] = *(const u32x4*)(Ag + (size_t)(64 * i) * K); rb[i] = *(const u32x4*)(Bg[i]); }
; #pragma unroll
;   for (int i = 0; i < 4; ++i) { *(u32x4*)(As0 + (srow + 64 * i) * LD + skc * 8) = ra[i]; *(u32x4*)(Bs0 + (srow + 64 * i) * LD + skc * 8) = rb[i]; }
;   if (nk > 1) {
; #pragma unroll
;     for (int i = 0; i < 4; ++i) { ra[i] = *(const u32x4*)(Ag + (size_t)(64 * i) * K + 64); rb[i] = *(const u32x4*)(Bg[i] + 64); }
;   }
;   for (int kt = 0; kt < nk; ++kt) {
;     __syncthreads();
;     if (kt + 1 < nk) {
;       u16* aw = As0 + ((kt + 1) & 1) * 256 * LD;
;       u16* bw = Bs0 + ((kt + 1) & 1) * 256 * LD;
; #pragma unroll
;       for (int i = 0; i < 4; ++i) { *(u32x4*)(aw + (srow + 64 * i) * LD + skc * 8) = ra[i]; *(u32x4*)(bw + (srow + 64 * i) * LD + skc * 8) = rb[i]; }
;     }
;     if (kt + 2 < nk) {
; #pragma unroll
;       for (int i = 0; i < 4; ++i) { ra[i] = *(const u32x4*)(Ag + (size_t)(64 * i) * K + (kt + 2) * 64); rb[i] = *(const u32x4*)(Bg[i] + (kt + 2) * 64); }
;     }
;     __builtin_amdgcn_sched_barrier(0);
;     const u16* as = As0 + (kt & 1) * 256 * LD + (wr * 128 + l31) * LD + h * 8;
;     const u16* bs = Bs0 + (kt & 1) * 256 * LD + (wc * 64 + l31) * LD + h * 8;
;     if (domma)
; #pragma unroll
;     for (int ks = 0; ks < 4; ++ks) {
;       bf16x8 wf[2], xf[4];
; #pragma unroll
;       for (int ct = 0; ct < 2; ++ct) wf[ct] = *(const bf16x8*)(bs + ct * 32 * LD + ks * 16);
; #pragma unroll
;       for (int tt = 0; tt < 4; ++tt) xf[tt] = *(const bf16x8*)(as + tt * 32 * LD + ks * 16);
; #pragma unroll
;       for (int ct = 0; ct < 2; ++ct)
; #pragma unroll
;         for (int tt = 0; tt < 4; ++tt) acc[ct][tt] = __builtin_amdgcn_mfma_f32_32x32x16_bf16(wf[ct], xf[tt], acc[ct][tt], 0, 0, 0);
;     }
	ds_write_b128 v250, v[52:55] offset:36864
	s_waitcnt vmcnt(18)
	ds_write_b128 v250, v[56:59] offset:46080
	s_waitcnt vmcnt(17)
	ds_write_b128 v250, v[60:63] offset:55296
	s_waitcnt vmcnt(16)
	ds_write_b128 v250, v[64:67] offset:64512
	ds_read_b128 v[210:213], v249
	ds_read_b128 v[236:239], v248
	ds_read_b128 v[214:217], v249 offset:4608
	ds_read_b128 v[2:5], v248 offset:4608
	ds_read_b128 v[6:9], v248 offset:9216
	ds_read_b128 v[10:13], v248 offset:13824
	s_waitcnt lgkmcnt(4)
	v_mfma_f32_32x32x16_bf16 v[114:129], v[210:213], v[236:239], 0
	ds_read_b128 v[228:231], v249 offset:32
	s_waitcnt lgkmcnt(4)
	v_mfma_f32_32x32x16_bf16 v[130:145], v[214:217], v[236:239], 0
	ds_read_b128 v[14:17], v248 offset:32
	s_waitcnt lgkmcnt(4)
	v_mfma_f32_32x32x16_bf16 v[82:97], v[210:213], v[2:5], 0
	ds_read_b128 v[232:235], v249 offset:4640
	v_mfma_f32_32x32x16_bf16 v[98:113], v[214:217], v[2:5], 0
	ds_read_b128 v[236:239], v248 offset:4640
	s_waitcnt lgkmcnt(5)
	v_mfma_f32_32x32x16_bf16 v[50:65], v[210:213], v[6:9], 0
	ds_read_b128 v[2:5], v248 offset:9248
	v_mfma_f32_32x32x16_bf16 v[66:81], v[214:217], v[6:9], 0
	s_waitcnt lgkmcnt(5)
	v_mfma_f32_32x32x16_bf16 v[18:33], v[210:213], v[10:13], 0
	ds_read_b128 v[6:9], v248 offset:13856
	v_mfma_f32_32x32x16_bf16 v[34:49], v[214:217], v[10:13], 0
	s_waitcnt lgkmcnt(4)
	v_mfma_f32_32x32x16_bf16 v[114:129], v[228:231], v[14:17], v[114:129]
	ds_read_b128 v[210:213], v249 offset:64
	s_waitcnt lgkmcnt(4)
	v_mfma_f32_32x32x16_bf16 v[130:145], v[232:235], v[14:17], v[130:145]
	ds_read_b128 v[10:13], v248 offset:64
	s_waitcnt lgkmcnt(4)
	v_mfma_f32_32x32x16_bf16 v[82:97], v[228:231], v[236:239], v[82:97]
	ds_read_b128 v[214:217], v249 offset:4672
	v_mfma_f32_32x32x16_bf16 v[98:113], v[232:235], v[236:239], v[98:113]
	ds_read_b128 v[14:17], v248 offset:4672
	s_waitcnt lgkmcnt(5)
	v_mfma_f32_32x32x16_bf16 v[50:65], v[228:231], v[2:5], v[50:65]
	ds_read_b128 v[236:239], v248 offset:9280
	v_mfma_f32_32x32x16_bf16 v[66:81], v[232:235], v[2:5], v[66:81]
	s_waitcnt lgkmcnt(5)
	v_mfma_f32_32x32x16_bf16 v[18:33], v[228:231], v[6:9], v[18:33]
	ds_read_b128 v[2:5], v248 offset:13888
	v_mfma_f32_32x32x16_bf16 v[34:49], v[232:235], v[6:9], v[34:49]
	s_waitcnt lgkmcnt(4)
	v_mfma_f32_32x32x16_bf16 v[114:129], v[210:213], v[10:13], v[114:129]
	ds_read_b128 v[228:231], v249 offset:96
	s_waitcnt lgkmcnt(4)
	v_mfma_f32_32x32x16_bf16 v[130:145], v[214:217], v[10:13], v[130:145]
	ds_read_b128 v[6:9], v248 offset:96
	s_waitcnt lgkmcnt(4)
	v_mfma_f32_32x32x16_bf16 v[82:97], v[210:213], v[14:17], v[82:97]
	ds_read_b128 v[232:235], v249 offset:4704
	v_mfma_f32_32x32x16_bf16 v[98:113], v[214:217], v[14:17], v[98:113]
	ds_read_b128 v[10:13], v248 offset:4704
	s_waitcnt lgkmcnt(5)
	v_mfma_f32_32x32x16_bf16 v[50:65], v[210:213], v[236:239], v[50:65]
	ds_read_b128 v[14:17], v248 offset:9312
	v_mfma_f32_32x32x16_bf16 v[66:81], v[214:217], v[236:239], v[66:81]
	s_waitcnt lgkmcnt(5)
	v_mfma_f32_32x32x16_bf16 v[18:33], v[210:213], v[2:5], v[18:33]
	ds_read_b128 v[236:239], v248 offset:13920
	v_mfma_f32_32x32x16_bf16 v[34:49], v[214:217], v[2:5], v[34:49]
	s_waitcnt lgkmcnt(4)
	v_mfma_f32_32x32x16_bf16 v[114:129], v[228:231], v[6:9], v[114:129]
	s_waitcnt lgkmcnt(3)
	v_mfma_f32_32x32x16_bf16 v[130:145], v[232:235], v[6:9], v[130:145]
	s_waitcnt lgkmcnt(2)
	v_mfma_f32_32x32x16_bf16 v[82:97], v[228:231], v[10:13], v[82:97]
	v_mfma_f32_32x32x16_bf16 v[98:113], v[232:235], v[10:13], v[98:113]
	s_waitcnt lgkmcnt(1)
	v_mfma_f32_32x32x16_bf16 v[50:65], v[228:231], v[14:17], v[50:65]
	v_mfma_f32_32x32x16_bf16 v[66:81], v[232:235], v[14:17], v[66:81]
	s_waitcnt lgkmcnt(0)
	v_mfma_f32_32x32x16_bf16 v[18:33], v[228:231], v[236:239], v[18:33]
	v_mfma_f32_32x32x16_bf16 v[34:49], v[232:235], v[236:239], v[34:49]
	s_barrier
	ds_read_b128 v[210:213], v249 offset:36864
	ds_read_b128 v[236:239], v248 offset:36864
	ds_read_b128 v[214:217], v249 offset:41472
	ds_read_b128 v[2:5], v248 offset:41472
	ds_read_b128 v[6:9], v248 offset:46080
	ds_read_b128 v[10:13], v248 offset:50688
	s_waitcnt lgkmcnt(4)
	v_mfma_f32_32x32x16_bf16 v[114:129], v[210:213], v[236:239], v[114:129]
	ds_read_b128 v[228:231], v249 offset:36896
	s_waitcnt lgkmcnt(4)
	v_mfma_f32_32x32x16_bf16 v[130:145], v[214:217], v[236:239], v[130:145]
	ds_read_b128 v[14:17], v248 offset:36896
	s_waitcnt lgkmcnt(4)
	v_mfma_f32_32x32x16_bf16 v[82:97], v[210:213], v[2:5], v[82:97]
	ds_read_b128 v[232:235], v249 offset:41504
	v_mfma_f32_32x32x16_bf16 v[98:113], v[214:217], v[2:5], v[98:113]
	ds_read_b128 v[236:239], v248 offset:41504
	s_waitcnt vmcnt(15)
	ds_write_b128 v250, v[146:149]
	s_waitcnt lgkmcnt(6)
	v_mfma_f32_32x32x16_bf16 v[50:65], v[210:213], v[6:9], v[50:65]
	ds_read_b128 v[2:5], v248 offset:46112
	v_mfma_f32_32x32x16_bf16 v[66:81], v[214:217], v[6:9], v[66:81]
	global_load_dwordx4 v[146:149], v227, s[74:75] offset:512
	s_waitcnt lgkmcnt(6)
	v_mfma_f32_32x32x16_bf16 v[18:33], v[210:213], v[10:13], v[18:33]
	ds_read_b128 v[6:9], v248 offset:50720
	s_waitcnt vmcnt(15)
	ds_write_b128 v251, v[178:181]
	v_mfma_f32_32x32x16_bf16 v[34:49], v[214:217], v[10:13], v[34:49]
	s_waitcnt lgkmcnt(6)
	v_mfma_f32_32x32x16_bf16 v[114:129], v[228:231], v[14:17], v[114:129]
	ds_read_b128 v[210:213], v249 offset:36928
	global_load_dwordx4 v[178:181], v227, s[82:83] offset:512
	s_waitcnt lgkmcnt(6)
	v_mfma_f32_32x32x16_bf16 v[130:145], v[232:235], v[14:17], v[130:145]
	ds_read_b128 v[10:13], v248 offset:36928
	s_waitcnt vmcnt(15)
	ds_write_b128 v250, v[150:153] offset:9216
	s_waitcnt lgkmcnt(7)
;     ...
;   for (int kt = 0; kt < nk; ++kt) {
;     __syncthreads();
;     if (kt + 1 < nk) {
;       u16* aw = As0 + ((kt + 1) & 1) * 256 * LD;
;       u16* bw = Bs0 + ((kt + 1) & 1) * 256 * LD;
; #pragma unroll
;       for (int i = 0; i < 4; ++i) { *(u32x4*)(aw + (srow + 64 * i) * LD + skc * 8) = ra[i]; *(u32x4*)(bw + (srow + 64 * i) * LD + skc * 8) = rb[i]; }
;     }
;     if (kt + 2 < nk) {
; #pragma unroll
;       for (int i = 0; i < 4; ++i) { ra[i] = *(const u32x4*)(Ag + (size_t)(64 * i) * K + (kt + 2) * 64); rb[i] = *(const u32x4*)(Bg[i] + (kt + 2) * 64); }
;     }
;     __builtin_amdgcn_sched_barrier(0);
;     const u16* as = As0 + (kt & 1) * 256 * LD + (wr * 128 + l31) * LD + h * 8;
;     const u16* bs = Bs0 + (kt & 1) * 256 * LD + (wc * 64 + l31) * LD + h * 8;
;     if (domma)
; #pragma unroll
;     for (int ks = 0; ks < 4; ++ks) {
;       bf16x8 wf[2], xf[4];
; #pragma unroll
;       for (int ct = 0; ct < 2; ++ct) wf[ct] = *(const bf16x8*)(bs + ct * 32 * LD + ks * 16);
; #pragma unroll
;       for (int tt = 0; tt < 4; ++tt) xf[tt] = *(const bf16x8*)(as + tt * 32 * LD + ks * 16);
; #pragma unroll
;       for (int ct = 0; ct < 2; ++ct)
; #pragma unroll
;         for (int tt = 0; tt < 4; ++tt) acc[ct][tt] = __builtin_amdgcn_mfma_f32_32x32x16_bf16(wf[ct], xf[tt], acc[ct][tt], 0, 0, 0);
;     }
;     __builtin_amdgcn_sched_barrier(0);
;   }
	v_mfma_f32_32x32x16_bf16 v[82:97], v[228:231], v[236:239], v[82:97]
	ds_read_b128 v[214:217], v249 offset:41536
	v_mfma_f32_32x32x16_bf16 v[98:113], v[232:235], v[236:239], v[98:113]
	ds_read_b128 v[14:17], v248 offset:41536
	global_load_dwordx4 v[150:153], v227, s[76:77] offset:512
	s_waitcnt lgkmcnt(7)
	v_mfma_f32_32x32x16_bf16 v[50:65], v[228:231], v[2:5], v[50:65]
	ds_read_b128 v[236:239], v248 offset:46144
	s_waitcnt vmcnt(15)
	ds_write_b128 v251, v[182:185] offset:9216
	v_mfma_f32_32x32x16_bf16 v[66:81], v[232:235], v[2:5], v[66:81]
	s_waitcnt lgkmcnt(8)
	v_mfma_f32_32x32x16_bf16 v[18:33], v[228:231], v[6:9], v[18:33]
	ds_read_b128 v[2:5], v248 offset:50752
	global_load_dwordx4 v[182:185], v227, s[84:85] offset:512
	v_mfma_f32_32x32x16_bf16 v[34:49], v[232:235], v[6:9], v[34:49]
	s_waitcnt vmcnt(15)
	ds_write_b128 v250, v[154:157] offset:18432
	s_waitcnt lgkmcnt(7)
	v_mfma_f32_32x32x16_bf16 v[114:129], v[210:213], v[10:13], v[114:129]
	ds_read_b128 v[228:231], v249 offset:36960
	s_waitcnt lgkmcnt(6)
	v_mfma_f32_32x32x16_bf16 v[130:145], v[214:217], v[10:13], v[130:145]
	ds_read_b128 v[6:9], v248 offset:36960
	global_load_dwordx4 v[154:157], v227, s[78:79] offset:512
	s_waitcnt lgkmcnt(6)
	v_mfma_f32_32x32x16_bf16 v[82:97], v[210:213], v[14:17], v[82:97]
	ds_read_b128 v[232:235], v249 offset:41568
	s_waitcnt vmcnt(15)
	ds_write_b128 v251, v[186:189] offset:18432
	v_mfma_f32_32x32x16_bf16 v[98:113], v[214:217], v[14:17], v[98:113]
	ds_read_b128 v[10:13], v248 offset:41568
	s_waitcnt lgkmcnt(8)
	v_mfma_f32_32x32x16_bf16 v[50:65], v[210:213], v[236:239], v[50:65]
	ds_read_b128 v[14:17], v248 offset:46176
	global_load_dwordx4 v[186:189], v227, s[86:87] offset:512
	v_mfma_f32_32x32x16_bf16 v[66:81], v[214:217], v[236:239], v[66:81]
	s_waitcnt vmcnt(15)
	ds_write_b128 v250, v[158:161] offset:27648
	s_waitcnt lgkmcnt(8)
	v_mfma_f32_32x32x16_bf16 v[18:33], v[210:213], v[2:5], v[18:33]
	ds_read_b128 v[236:239], v248 offset:50784
	v_mfma_f32_32x32x16_bf16 v[34:49], v[214:217], v[2:5], v[34:49]
	global_load_dwordx4 v[158:161], v227, s[80:81] offset:512
	s_waitcnt lgkmcnt(6)
	v_mfma_f32_32x32x16_bf16 v[114:129], v[228:231], v[6:9], v[114:129]
	s_waitcnt vmcnt(15)
	ds_write_b128 v251, v[190:193] offset:27648
	s_waitcnt lgkmcnt(6)
	v_mfma_f32_32x32x16_bf16 v[130:145], v[232:235], v[6:9], v[130:145]
	s_waitcnt lgkmcnt(4)
	v_mfma_f32_32x32x16_bf16 v[82:97], v[228:231], v[10:13], v[82:97]
	global_load_dwordx4 v[190:193], v227, s[92:93] offset:512
	v_mfma_f32_32x32x16_bf16 v[98:113], v[232:235], v[10:13], v[98:113]
	s_waitcnt lgkmcnt(3)
	v_mfma_f32_32x32x16_bf16 v[50:65], v[228:231], v[14:17], v[50:65]
	v_mfma_f32_32x32x16_bf16 v[66:81], v[232:235], v[14:17], v[66:81]
	s_waitcnt lgkmcnt(1)
	v_mfma_f32_32x32x16_bf16 v[18:33], v[228:231], v[236:239], v[18:33]
	v_mfma_f32_32x32x16_bf16 v[34:49], v[232:235], v[236:239], v[34:49]
	s_waitcnt lgkmcnt(0)
	s_barrier
	ds_read_b128 v[210:213], v249
	ds_read_b128 v[236:239], v248
	ds_read_b128 v[214:217], v249 offset:4608
	ds_read_b128 v[2:5], v248 offset:4608
	ds_read_b128 v[6:9], v248 offset:9216
	ds_read_b128 v[10:13], v248 offset:13824
	s_waitcnt lgkmcnt(4)
	v_mfma_f32_32x32x16_bf16 v[114:129], v[210:213], v[236:239], v[114:129]
	ds_read_b128 v[228:231], v249 offset:32
	s_waitcnt lgkmcnt(4)
	v_mfma_f32_32x32x16_bf16 v[130:145], v[214:217], v[236:239], v[130:145]
	ds_read_b128 v[14:17], v248 offset:32
	s_waitcnt lgkmcnt(4)
	v_mfma_f32_32x32x16_bf16 v[82:97], v[210:213], v[2:5], v[82:97]
	ds_read_b128 v[232:235], v249 offset:4640
	v_mfma_f32_32x32x16_bf16 v[98:113], v[214:217], v[2:5], v[98:113]
	ds_read_b128 v[236:239], v248 offset:4640
	s_waitcnt vmcnt(15)
	ds_write_b128 v250, v[162:165] offset:36864
	s_waitcnt lgkmcnt(6)
	v_mfma_f32_32x32x16_bf16 v[50:65], v[210:213], v[6:9], v[50:65]
	ds_read_b128 v[2:5], v248 offset:9248
	v_mfma_f32_32x32x16_bf16 v[66:81], v[214:217], v[6:9], v[66:81]
	global_load_dwordx4 v[162:165], v227, s[74:75] offset:640
	s_waitcnt lgkmcnt(6)
	v_mfma_f32_32x32x16_bf16 v[18:33], v[210:213], v[10:13], v[18:33]
	ds_read_b128 v[6:9], v248 offset:13856
	s_waitcnt vmcnt(15)
	ds_write_b128 v251, v[194:197] offset:36864
	v_mfma_f32_32x32x16_bf16 v[34:49], v[214:217], v[10:13], v[34:49]
	s_waitcnt lgkmcnt(6)
	v_mfma_f32_32x32x16_bf16 v[114:129], v[228:231], v[14:17], v[114:129]
	ds_read_b128 v[210:213], v249 offset:64
	global_load_dwordx4 v[194:197], v227, s[82:83] offset:640
	s_waitcnt lgkmcnt(6)
	v_mfma_f32_32x32x16_bf16 v[130:145], v[232:235], v[14:17], v[130:145]
	ds_read_b128 v[10:13], v248 offset:64
	s_waitcnt vmcnt(15)
	ds_write_b128 v250, v[166:169] offset:46080
	s_waitcnt lgkmcnt(7)
	v_mfma_f32_32x32x16_bf16 v[82:97], v[228:231], v[236:239], v[82:97]
	ds_read_b128 v[214:217], v249 offset:4672
	v_mfma_f32_32x32x16_bf16 v[98:113], v[232:235], v[236:239], v[98:113]
	ds_read_b128 v[14:17], v248 offset:4672
	global_load_dwordx4 v[166:169], v227, s[76:77] offset:640
	s_waitcnt lgkmcnt(7)
	v_mfma_f32_32x32x16_bf16 v[50:65], v[228:231], v[2:5], v[50:65]
	ds_read_b128 v[236:239], v248 offset:9280
	s_waitcnt vmcnt(15)
	ds_write_b128 v251, v[198:201] offset:46080
	v_mfma_f32_32x32x16_bf16 v[66:81], v[232:235], v[2:5], v[66:81]
	s_waitcnt lgkmcnt(8)
	v_mfma_f32_32x32x16_bf16 v[18:33], v[228:231], v[6:9], v[18:33]
	ds_read_b128 v[2:5], v248 offset:13888
	global_load_dwordx4 v[198:201], v227, s[84:85] offset:640
	v_mfma_f32_32x32x16_bf16 v[34:49], v[232:235], v[6:9], v[34:49]
	s_waitcnt vmcnt(15)
	ds_write_b128 v250, v[170:173] offset:55296
	s_waitcnt lgkmcnt(7)
	v_mfma_f32_32x32x16_bf16 v[114:129], v[210:213], v[10:13], v[114:129]
	ds_read_b128 v[228:231], v249 offset:96
	s_waitcnt lgkmcnt(6)
;     ...
;   for (int kt = 0; kt < nk; ++kt) {
;     __syncthreads();
;     if (kt + 1 < nk) {
;       u16* aw = As0 + ((kt + 1) & 1) * 256 * LD;
;       u16* bw = Bs0 + ((kt + 1) & 1) * 256 * LD;
; #pragma unroll
;       for (int i = 0; i < 4; ++i) { *(u32x4*)(aw + (srow + 64 * i) * LD + skc * 8) = ra[i]; *(u32x4*)(bw + (srow + 64 * i) * LD + skc * 8) = rb[i]; }
;     }
;     if (kt + 2 < nk) {
; #pragma unroll
;       for (int i = 0; i < 4; ++i) { ra[i] = *(const u32x4*)(Ag + (size_t)(64 * i) * K + (kt + 2) * 64); rb[i] = *(const u32x4*)(Bg[i] + (kt + 2) * 64); }
;     }
;     __builtin_amdgcn_sched_barrier(0);
;     const u16* as = As0 + (kt & 1) * 256 * LD + (wr * 128 + l31) * LD + h * 8;
;     const u16* bs = Bs0 + (kt & 1) * 256 * LD + (wc * 64 + l31) * LD + h * 8;
;     if (domma)
; #pragma unroll
;     for (int ks = 0; ks < 4; ++ks) {
;       bf16x8 wf[2], xf[4];
; #pragma unroll
;       for (int ct = 0; ct < 2; ++ct) wf[ct] = *(const bf16x8*)(bs + ct * 32 * LD + ks * 16);
; #pragma unroll
;       for (int tt = 0; tt < 4; ++tt) xf[tt] = *(const bf16x8*)(as + tt * 32 * LD + ks * 16);
; #pragma unroll
;       for (int ct = 0; ct < 2; ++ct)
; #pragma unroll
;         for (int tt = 0; tt < 4; ++tt) acc[ct][tt] = __builtin_amdgcn_mfma_f32_32x32x16_bf16(wf[ct], xf[tt], acc[ct][tt], 0, 0, 0);
;     }
;     __builtin_amdgcn_sched_barrier(0);
;   }
	v_mfma_f32_32x32x16_bf16 v[130:145], v[214:217], v[10:13], v[130:145]
	ds_read_b128 v[6:9], v248 offset:96
	global_load_dwordx4 v[170:173], v227, s[78:79] offset:640
	s_waitcnt lgkmcnt(6)
	v_mfma_f32_32x32x16_bf16 v[82:97], v[210:213], v[14:17], v[82:97]
	ds_read_b128 v[232:235], v249 offset:4704
	s_waitcnt vmcnt(15)
	ds_write_b128 v251, v[202:205] offset:55296
	v_mfma_f32_32x32x16_bf16 v[98:113], v[214:217], v[14:17], v[98:113]
	ds_read_b128 v[10:13], v248 offset:4704
	s_waitcnt lgkmcnt(8)
	v_mfma_f32_32x32x16_bf16 v[50:65], v[210:213], v[236:239], v[50:65]
	ds_read_b128 v[14:17], v248 offset:9312
	global_load_dwordx4 v[202:205], v227, s[86:87] offset:640
	v_mfma_f32_32x32x16_bf16 v[66:81], v[214:217], v[236:239], v[66:81]
	s_waitcnt vmcnt(15)
	ds_write_b128 v250, v[174:177] offset:64512
	s_waitcnt lgkmcnt(8)
	v_mfma_f32_32x32x16_bf16 v[18:33], v[210:213], v[2:5], v[18:33]
	ds_read_b128 v[236:239], v248 offset:13920
	v_mfma_f32_32x32x16_bf16 v[34:49], v[214:217], v[2:5], v[34:49]
	global_load_dwordx4 v[174:177], v227, s[80:81] offset:640
	s_waitcnt lgkmcnt(6)
	v_mfma_f32_32x32x16_bf16 v[114:129], v[228:231], v[6:9], v[114:129]
	s_waitcnt vmcnt(15)
	ds_write_b128 v251, v[206:209] offset:64512
	s_waitcnt lgkmcnt(6)
	v_mfma_f32_32x32x16_bf16 v[130:145], v[232:235], v[6:9], v[130:145]
	s_waitcnt lgkmcnt(4)
	v_mfma_f32_32x32x16_bf16 v[82:97], v[228:231], v[10:13], v[82:97]
	global_load_dwordx4 v[206:209], v227, s[92:93] offset:640
	v_mfma_f32_32x32x16_bf16 v[98:113], v[232:235], v[10:13], v[98:113]
	s_waitcnt lgkmcnt(3)
	v_mfma_f32_32x32x16_bf16 v[50:65], v[228:231], v[14:17], v[50:65]
	v_mfma_f32_32x32x16_bf16 v[66:81], v[232:235], v[14:17], v[66:81]
	s_waitcnt lgkmcnt(1)
	v_mfma_f32_32x32x16_bf16 v[18:33], v[228:231], v[236:239], v[18:33]
	v_mfma_f32_32x32x16_bf16 v[34:49], v[232:235], v[236:239], v[34:49]
	s_waitcnt lgkmcnt(0)
	s_barrier
	ds_read_b128 v[210:213], v249 offset:36864
	ds_read_b128 v[236:239], v248 offset:36864
	ds_read_b128 v[214:217], v249 offset:41472
	ds_read_b128 v[2:5], v248 offset:41472
	ds_read_b128 v[6:9], v248 offset:46080
	ds_read_b128 v[10:13], v248 offset:50688
	s_waitcnt lgkmcnt(4)
	v_mfma_f32_32x32x16_bf16 v[114:129], v[210:213], v[236:239], v[114:129]
	ds_read_b128 v[228:231], v249 offset:36896
	s_waitcnt lgkmcnt(4)
	v_mfma_f32_32x32x16_bf16 v[130:145], v[214:217], v[236:239], v[130:145]
	ds_read_b128 v[14:17], v248 offset:36896
	s_waitcnt lgkmcnt(4)
	v_mfma_f32_32x32x16_bf16 v[82:97], v[210:213], v[2:5], v[82:97]
	ds_read_b128 v[232:235], v249 offset:41504
	v_mfma_f32_32x32x16_bf16 v[98:113], v[214:217], v[2:5], v[98:113]
	ds_read_b128 v[236:239], v248 offset:41504
	s_waitcnt vmcnt(15)
	ds_write_b128 v250, v[146:149]
	s_waitcnt lgkmcnt(6)
	v_mfma_f32_32x32x16_bf16 v[50:65], v[210:213], v[6:9], v[50:65]
	ds_read_b128 v[2:5], v248 offset:46112
	v_mfma_f32_32x32x16_bf16 v[66:81], v[214:217], v[6:9], v[66:81]
	global_load_dwordx4 v[146:149], v227, s[74:75] offset:768
	s_waitcnt lgkmcnt(6)
	v_mfma_f32_32x32x16_bf16 v[18:33], v[210:213], v[10:13], v[18:33]
	ds_read_b128 v[6:9], v248 offset:50720
	s_waitcnt vmcnt(15)
	ds_write_b128 v251, v[178:181]
	v_mfma_f32_32x32x16_bf16 v[34:49], v[214:217], v[10:13], v[34:49]
	s_waitcnt lgkmcnt(6)
	v_mfma_f32_32x32x16_bf16 v[114:129], v[228:231], v[14:17], v[114:129]
	ds_read_b128 v[210:213], v249 offset:36928
	global_load_dwordx4 v[178:181], v227, s[82:83] offset:768
	s_waitcnt lgkmcnt(6)
	v_mfma_f32_32x32x16_bf16 v[130:145], v[232:235], v[14:17], v[130:145]
	ds_read_b128 v[10:13], v248 offset:36928
	s_waitcnt vmcnt(15)
	ds_write_b128 v250, v[150:153] offset:9216
	s_waitcnt lgkmcnt(7)
	v_mfma_f32_32x32x16_bf16 v[82:97], v[228:231], v[236:239], v[82:97]
	ds_read_b128 v[214:217], v249 offset:41536
	v_mfma_f32_32x32x16_bf16 v[98:113], v[232:235], v[236:239], v[98:113]
	ds_read_b128 v[14:17], v248 offset:41536
	global_load_dwordx4 v[150:153], v227, s[76:77] offset:768
	s_waitcnt lgkmcnt(7)
	v_mfma_f32_32x32x16_bf16 v[50:65], v[228:231], v[2:5], v[50:65]
	ds_read_b128 v[236:239], v248 offset:46144
	s_waitcnt vmcnt(15)
	ds_write_b128 v251, v[182:185] offset:9216
	v_mfma_f32_32x32x16_bf16 v[66:81], v[232:235], v[2:5], v[66:81]
	s_waitcnt lgkmcnt(8)
	v_mfma_f32_32x32x16_bf16 v[18:33], v[228:231], v[6:9], v[18:33]
	ds_read_b128 v[2:5], v248 offset:50752
	global_load_dwordx4 v[182:185], v227, s[84:85] offset:768
	v_mfma_f32_32x32x16_bf16 v[34:49], v[232:235], v[6:9], v[34:49]
	s_waitcnt vmcnt(15)
	ds_write_b128 v250, v[154:157] offset:18432
	s_waitcnt lgkmcnt(7)
	v_mfma_f32_32x32x16_bf16 v[114:129], v[210:213], v[10:13], v[114:129]
	ds_read_b128 v[228:231], v249 offset:36960
	s_waitcnt lgkmcnt(6)
	v_mfma_f32_32x32x16_bf16 v[130:145], v[214:217], v[10:13], v[130:145]
	ds_read_b128 v[6:9], v248 offset:36960
	global_load_dwordx4 v[154:157], v227, s[78:79] offset:768
	s_waitcnt lgkmcnt(6)
	v_mfma_f32_32x32x16_bf16 v[82:97], v[210:213], v[14:17], v[82:97]
	ds_read_b128 v[232:235], v249 offset:41568
	s_waitcnt vmcnt(15)
	ds_write_b128 v251, v[186:189] offset:18432
	v_mfma_f32_32x32x16_bf16 v[98:113], v[214:217], v[14:17], v[98:113]
	ds_read_b128 v[10:13], v248 offset:41568
	s_waitcnt lgkmcnt(8)
	v_mfma_f32_32x32x16_bf16 v[50:65], v[210:213], v[236:239], v[50:65]
	ds_read_b128 v[14:17], v248 offset:46176
	global_load_dwordx4 v[186:189], v227, s[86:87] offset:768
	v_mfma_f32_32x32x16_bf16 v[66:81], v[214:217], v[236:239], v[66:81]
	s_waitcnt vmcnt(15)
	ds_write_b128 v250, v[158:161] offset:27648
	s_waitcnt lgkmcnt(8)
	v_mfma_f32_32x32x16_bf16 v[18:33], v[210:213], v[2:5], v[18:33]
	ds_read_b128 v[236:239], v248 offset:50784
	v_mfma_f32_32x32x16_bf16 v[34:49], v[214:217], v[2:5], v[34:49]
	global_load_dwordx4 v[158:161], v227, s[80:81] offset:768
	s_waitcnt lgkmcnt(6)
	v_mfma_f32_32x32x16_bf16 v[114:129], v[228:231], v[6:9], v[114:129]
	s_waitcnt vmcnt(15)
	ds_write_b128 v251, v[190:193] offset:27648
	s_waitcnt lgkmcnt(6)
	v_mfma_f32_32x32x16_bf16 v[130:145], v[232:235], v[6:9], v[130:145]
	s_waitcnt lgkmcnt(4)
	v_mfma_f32_32x32x16_bf16 v[82:97], v[228:231], v[10:13], v[82:97]
	global_load_dwordx4 v[190:193], v227, s[92:93] offset:768
	v_mfma_f32_32x32x16_bf16 v[98:113], v[232:235], v[10:13], v[98:113]
	s_waitcnt lgkmcnt(3)
	v_mfma_f32_32x32x16_bf16 v[50:65], v[228:231], v[14:17], v[50:65]
	v_mfma_f32_32x32x16_bf16 v[66:81], v[232:235], v[14:17], v[66:81]
	s_waitcnt lgkmcnt(1)
	v_mfma_f32_32x32x16_bf16 v[18:33], v[228:231], v[236:239], v[18:33]
	v_mfma_f32_32x32x16_bf16 v[34:49], v[232:235], v[236:239], v[34:49]
	s_waitcnt lgkmcnt(0)
	s_barrier
;     ...
;   for (int kt = 0; kt < nk; ++kt) {
;     __syncthreads();
;     if (kt + 1 < nk) {
;       u16* aw = As0 + ((kt + 1) & 1) * 256 * LD;
;       u16* bw = Bs0 + ((kt + 1) & 1) * 256 * LD;
; #pragma unroll
;       for (int i = 0; i < 4; ++i) { *(u32x4*)(aw + (srow + 64 * i) * LD + skc * 8) = ra[i]; *(u32x4*)(bw + (srow + 64 * i) * LD + skc * 8) = rb[i]; }
;     }
;     if (kt + 2 < nk) {
; #pragma unroll
;       for (int i = 0; i < 4; ++i) { ra[i] = *(const u32x4*)(Ag + (size_t)(64 * i) * K + (kt + 2) * 64); rb[i] = *(const u32x4*)(Bg[i] + (kt + 2) * 64); }
;     }
;     __builtin_amdgcn_sched_barrier(0);
;     const u16* as = As0 + (kt & 1) * 256 * LD + (wr * 128 + l31) * LD + h * 8;
;     const u16* bs = Bs0 + (kt & 1) * 256 * LD + (wc * 64 + l31) * LD + h * 8;
;     if (domma)
; #pragma unroll
;     for (int ks = 0; ks < 4; ++ks) {
;       bf16x8 wf[2], xf[4];
; #pragma unroll
;       for (int ct = 0; ct < 2; ++ct) wf[ct] = *(const bf16x8*)(bs + ct * 32 * LD + ks * 16);
; #pragma unroll
;       for (int tt = 0; tt < 4; ++tt) xf[tt] = *(const bf16x8*)(as + tt * 32 * LD + ks * 16);
; #pragma unroll
;       for (int ct = 0; ct < 2; ++ct)
; #pragma unroll
;         for (int tt = 0; tt < 4; ++tt) acc[ct][tt] = __builtin_amdgcn_mfma_f32_32x32x16_bf16(wf[ct], xf[tt], acc[ct][tt], 0, 0, 0);
;     }
	ds_read_b128 v[210:213], v249
	ds_read_b128 v[236:239], v248
	ds_read_b128 v[214:217], v249 offset:4608
	ds_read_b128 v[2:5], v248 offset:4608
	ds_read_b128 v[6:9], v248 offset:9216
	ds_read_b128 v[10:13], v248 offset:13824
	s_waitcnt lgkmcnt(4)
	v_mfma_f32_32x32x16_bf16 v[114:129], v[210:213], v[236:239], v[114:129]
	ds_read_b128 v[228:231], v249 offset:32
	s_waitcnt lgkmcnt(4)
	v_mfma_f32_32x32x16_bf16 v[130:145], v[214:217], v[236:239], v[130:145]
	ds_read_b128 v[14:17], v248 offset:32
	s_waitcnt lgkmcnt(4)
	v_mfma_f32_32x32x16_bf16 v[82:97], v[210:213], v[2:5], v[82:97]
	ds_read_b128 v[232:235], v249 offset:4640
	v_mfma_f32_32x32x16_bf16 v[98:113], v[214:217], v[2:5], v[98:113]
	ds_read_b128 v[236:239], v248 offset:4640
	s_waitcnt vmcnt(15)
	ds_write_b128 v250, v[162:165] offset:36864
	s_waitcnt lgkmcnt(6)
	v_mfma_f32_32x32x16_bf16 v[50:65], v[210:213], v[6:9], v[50:65]
	ds_read_b128 v[2:5], v248 offset:9248
	v_mfma_f32_32x32x16_bf16 v[66:81], v[214:217], v[6:9], v[66:81]
	global_load_dwordx4 v[162:165], v227, s[74:75] offset:896
	s_waitcnt lgkmcnt(6)
	v_mfma_f32_32x32x16_bf16 v[18:33], v[210:213], v[10:13], v[18:33]
	ds_read_b128 v[6:9], v248 offset:13856
	s_waitcnt vmcnt(15)
	ds_write_b128 v251, v[194:197] offset:36864
	v_mfma_f32_32x32x16_bf16 v[34:49], v[214:217], v[10:13], v[34:49]
	s_waitcnt lgkmcnt(6)
	v_mfma_f32_32x32x16_bf16 v[114:129], v[228:231], v[14:17], v[114:129]
	ds_read_b128 v[210:213], v249 offset:64
	global_load_dwordx4 v[194:197], v227, s[82:83] offset:896
	s_waitcnt lgkmcnt(6)
	v_mfma_f32_32x32x16_bf16 v[130:145], v[232:235], v[14:17], v[130:145]
	ds_read_b128 v[10:13], v248 offset:64
	s_waitcnt vmcnt(15)
	ds_write_b128 v250, v[166:169] offset:46080
	s_waitcnt lgkmcnt(7)
	v_mfma_f32_32x32x16_bf16 v[82:97], v[228:231], v[236:239], v[82:97]
	ds_read_b128 v[214:217], v249 offset:4672
	v_mfma_f32_32x32x16_bf16 v[98:113], v[232:235], v[236:239], v[98:113]
	ds_read_b128 v[14:17], v248 offset:4672
	global_load_dwordx4 v[166:169], v227, s[76:77] offset:896
	s_waitcnt lgkmcnt(7)
	v_mfma_f32_32x32x16_bf16 v[50:65], v[228:231], v[2:5], v[50:65]
	ds_read_b128 v[236:239], v248 offset:9280
	s_waitcnt vmcnt(15)
	ds_write_b128 v251, v[198:201] offset:46080
	v_mfma_f32_32x32x16_bf16 v[66:81], v[232:235], v[2:5], v[66:81]
	s_waitcnt lgkmcnt(8)
	v_mfma_f32_32x32x16_bf16 v[18:33], v[228:231], v[6:9], v[18:33]
	ds_read_b128 v[2:5], v248 offset:13888
	global_load_dwordx4 v[198:201], v227, s[84:85] offset:896
	v_mfma_f32_32x32x16_bf16 v[34:49], v[232:235], v[6:9], v[34:49]
	s_waitcnt vmcnt(15)
	ds_write_b128 v250, v[170:173] offset:55296
	s_waitcnt lgkmcnt(7)
	v_mfma_f32_32x32x16_bf16 v[114:129], v[210:213], v[10:13], v[114:129]
	ds_read_b128 v[228:231], v249 offset:96
	s_waitcnt lgkmcnt(6)
	v_mfma_f32_32x32x16_bf16 v[130:145], v[214:217], v[10:13], v[130:145]
	ds_read_b128 v[6:9], v248 offset:96
	global_load_dwordx4 v[170:173], v227, s[78:79] offset:896
	s_waitcnt lgkmcnt(6)
	v_mfma_f32_32x32x16_bf16 v[82:97], v[210:213], v[14:17], v[82:97]
	ds_read_b128 v[232:235], v249 offset:4704
	s_waitcnt vmcnt(15)
	ds_write_b128 v251, v[202:205] offset:55296
	v_mfma_f32_32x32x16_bf16 v[98:113], v[214:217], v[14:17], v[98:113]
	ds_read_b128 v[10:13], v248 offset:4704
	s_waitcnt lgkmcnt(8)
	v_mfma_f32_32x32x16_bf16 v[50:65], v[210:213], v[236:239], v[50:65]
	ds_read_b128 v[14:17], v248 offset:9312
	global_load_dwordx4 v[202:205], v227, s[86:87] offset:896
	v_mfma_f32_32x32x16_bf16 v[66:81], v[214:217], v[236:239], v[66:81]
	s_waitcnt vmcnt(15)
	ds_write_b128 v250, v[174:177] offset:64512
	s_waitcnt lgkmcnt(8)
	v_mfma_f32_32x32x16_bf16 v[18:33], v[210:213], v[2:5], v[18:33]
	ds_read_b128 v[236:239], v248 offset:13920
	v_mfma_f32_32x32x16_bf16 v[34:49], v[214:217], v[2:5], v[34:49]
	global_load_dwordx4 v[174:177], v227, s[80:81] offset:896
	s_waitcnt lgkmcnt(6)
	v_mfma_f32_32x32x16_bf16 v[114:129], v[228:231], v[6:9], v[114:129]
	s_waitcnt vmcnt(15)
	ds_write_b128 v251, v[206:209] offset:64512
	s_waitcnt lgkmcnt(6)
	v_mfma_f32_32x32x16_bf16 v[130:145], v[232:235], v[6:9], v[130:145]
	s_waitcnt lgkmcnt(4)
	v_mfma_f32_32x32x16_bf16 v[82:97], v[228:231], v[10:13], v[82:97]
	global_load_dwordx4 v[206:209], v227, s[92:93] offset:896
	v_mfma_f32_32x32x16_bf16 v[98:113], v[232:235], v[10:13], v[98:113]
	s_waitcnt lgkmcnt(3)
	v_mfma_f32_32x32x16_bf16 v[50:65], v[228:231], v[14:17], v[50:65]
	v_mfma_f32_32x32x16_bf16 v[66:81], v[232:235], v[14:17], v[66:81]
	s_waitcnt lgkmcnt(1)
	v_mfma_f32_32x32x16_bf16 v[18:33], v[228:231], v[236:239], v[18:33]
	v_mfma_f32_32x32x16_bf16 v[34:49], v[232:235], v[236:239], v[34:49]
	s_waitcnt lgkmcnt(0)
	s_barrier
;     ...
;   for (int kt = 0; kt < nk; ++kt) {
;     __syncthreads();
;     if (kt + 1 < nk) {
;       u16* aw = As0 + ((kt + 1) & 1) * 256 * LD;
;       u16* bw = Bs0 + ((kt + 1) & 1) * 256 * LD;
; #pragma unroll
;       for (int i = 0; i < 4; ++i) { *(u32x4*)(aw + (srow + 64 * i) * LD + skc * 8) = ra[i]; *(u32x4*)(bw + (srow + 64 * i) * LD + skc * 8) = rb[i]; }
;     }
;     if (kt + 2 < nk) {
; #pragma unroll
;       for (int i = 0; i < 4; ++i) { ra[i] = *(const u32x4*)(Ag + (size_t)(64 * i) * K + (kt + 2) * 64); rb[i] = *(const u32x4*)(Bg[i] + (kt + 2) * 64); }
;     }
;     __builtin_amdgcn_sched_barrier(0);
;     const u16* as = As0 + (kt & 1) * 256 * LD + (wr * 128 + l31) * LD + h * 8;
;     const u16* bs = Bs0 + (kt & 1) * 256 * LD + (wc * 64 + l31) * LD + h * 8;
;     if (domma)
; #pragma unroll
;     for (int ks = 0; ks < 4; ++ks) {
;       bf16x8 wf[2], xf[4];
; #pragma unroll
;       for (int ct = 0; ct < 2; ++ct) wf[ct] = *(const bf16x8*)(bs + ct * 32 * LD + ks * 16);
; #pragma unroll
;       for (int tt = 0; tt < 4; ++tt) xf[tt] = *(const bf16x8*)(as + tt * 32 * LD + ks * 16);
; #pragma unroll
;       for (int ct = 0; ct < 2; ++ct)
; #pragma unroll
;         for (int tt = 0; tt < 4; ++tt) acc[ct][tt] = __builtin_amdgcn_mfma_f32_32x32x16_bf16(wf[ct], xf[tt], acc[ct][tt], 0, 0, 0);
;     }
	ds_read_b128 v[210:213], v249 offset:36864
	ds_read_b128 v[236:239], v248 offset:36864
	ds_read_b128 v[214:217], v249 offset:41472
	ds_read_b128 v[2:5], v248 offset:41472
	ds_read_b128 v[6:9], v248 offset:46080
	ds_read_b128 v[10:13], v248 offset:50688
	s_waitcnt lgkmcnt(4)
	v_mfma_f32_32x32x16_bf16 v[114:129], v[210:213], v[236:239], v[114:129]
	ds_read_b128 v[228:231], v249 offset:36896
	s_waitcnt lgkmcnt(4)
	v_mfma_f32_32x32x16_bf16 v[130:145], v[214:217], v[236:239], v[130:145]
	ds_read_b128 v[14:17], v248 offset:36896
	s_waitcnt lgkmcnt(4)
	v_mfma_f32_32x32x16_bf16 v[82:97], v[210:213], v[2:5], v[82:97]
	ds_read_b128 v[232:235], v249 offset:41504
	v_mfma_f32_32x32x16_bf16 v[98:113], v[214:217], v[2:5], v[98:113]
	ds_read_b128 v[236:239], v248 offset:41504
	s_waitcnt vmcnt(15)
	ds_write_b128 v250, v[146:149]
	s_waitcnt lgkmcnt(6)
	v_mfma_f32_32x32x16_bf16 v[50:65], v[210:213], v[6:9], v[50:65]
	ds_read_b128 v[2:5], v248 offset:46112
	v_mfma_f32_32x32x16_bf16 v[66:81], v[214:217], v[6:9], v[66:81]
	global_load_dwordx4 v[146:149], v227, s[74:75] offset:1024
	s_waitcnt lgkmcnt(6)
	v_mfma_f32_32x32x16_bf16 v[18:33], v[210:213], v[10:13], v[18:33]
	ds_read_b128 v[6:9], v248 offset:50720
	s_waitcnt vmcnt(15)
	ds_write_b128 v251, v[178:181]
	v_mfma_f32_32x32x16_bf16 v[34:49], v[214:217], v[10:13], v[34:49]
	s_waitcnt lgkmcnt(6)
	v_mfma_f32_32x32x16_bf16 v[114:129], v[228:231], v[14:17], v[114:129]
	ds_read_b128 v[210:213], v249 offset:36928
	global_load_dwordx4 v[178:181], v227, s[82:83] offset:1024
	s_waitcnt lgkmcnt(6)
	v_mfma_f32_32x32x16_bf16 v[130:145], v[232:235], v[14:17], v[130:145]
	ds_read_b128 v[10:13], v248 offset:36928
	s_waitcnt vmcnt(15)
	ds_write_b128 v250, v[150:153] offset:9216
	s_waitcnt lgkmcnt(7)
	v_mfma_f32_32x32x16_bf16 v[82:97], v[228:231], v[236:239], v[82:97]
	ds_read_b128 v[214:217], v249 offset:41536
	v_mfma_f32_32x32x16_bf16 v[98:113], v[232:235], v[236:239], v[98:113]
	ds_read_b128 v[14:17], v248 offset:41536
	global_load_dwordx4 v[150:153], v227, s[76:77] offset:1024
	s_waitcnt lgkmcnt(7)
	v_mfma_f32_32x32x16_bf16 v[50:65], v[228:231], v[2:5], v[50:65]
	ds_read_b128 v[236:239], v248 offset:46144
	s_waitcnt vmcnt(15)
	ds_write_b128 v251, v[182:185] offset:9216
	v_mfma_f32_32x32x16_bf16 v[66:81], v[232:235], v[2:5], v[66:81]
	s_waitcnt lgkmcnt(8)
	v_mfma_f32_32x32x16_bf16 v[18:33], v[228:231], v[6:9], v[18:33]
	ds_read_b128 v[2:5], v248 offset:50752
	global_load_dwordx4 v[182:185], v227, s[84:85] offset:1024
	v_mfma_f32_32x32x16_bf16 v[34:49], v[232:235], v[6:9], v[34:49]
	s_waitcnt vmcnt(15)
	ds_write_b128 v250, v[154:157] offset:18432
	s_waitcnt lgkmcnt(7)
	v_mfma_f32_32x32x16_bf16 v[114:129], v[210:213], v[10:13], v[114:129]
	ds_read_b128 v[228:231], v249 offset:36960
	s_waitcnt lgkmcnt(6)
	v_mfma_f32_32x32x16_bf16 v[130:145], v[214:217], v[10:13], v[130:145]
	ds_read_b128 v[6:9], v248 offset:36960
	global_load_dwordx4 v[154:157], v227, s[78:79] offset:1024
	s_waitcnt lgkmcnt(6)
	v_mfma_f32_32x32x16_bf16 v[82:97], v[210:213], v[14:17], v[82:97]
	ds_read_b128 v[232:235], v249 offset:41568
	s_waitcnt vmcnt(15)
	ds_write_b128 v251, v[186:189] offset:18432
	v_mfma_f32_32x32x16_bf16 v[98:113], v[214:217], v[14:17], v[98:113]
	ds_read_b128 v[10:13], v248 offset:41568
	s_waitcnt lgkmcnt(8)
	v_mfma_f32_32x32x16_bf16 v[50:65], v[210:213], v[236:239], v[50:65]
	ds_read_b128 v[14:17], v248 offset:46176
	global_load_dwordx4 v[186:189], v227, s[86:87] offset:1024
	v_mfma_f32_32x32x16_bf16 v[66:81], v[214:217], v[236:239], v[66:81]
	s_waitcnt vmcnt(15)
	ds_write_b128 v250, v[158:161] offset:27648
	s_waitcnt lgkmcnt(8)
	v_mfma_f32_32x32x16_bf16 v[18:33], v[210:213], v[2:5], v[18:33]
	ds_read_b128 v[236:239], v248 offset:50784
	v_mfma_f32_32x32x16_bf16 v[34:49], v[214:217], v[2:5], v[34:49]
	global_load_dwordx4 v[158:161], v227, s[80:81] offset:1024
	s_waitcnt lgkmcnt(6)
	v_mfma_f32_32x32x16_bf16 v[114:129], v[228:231], v[6:9], v[114:129]
	s_waitcnt vmcnt(15)
	ds_write_b128 v251, v[190:193] offset:27648
	s_waitcnt lgkmcnt(6)
	v_mfma_f32_32x32x16_bf16 v[130:145], v[232:235], v[6:9], v[130:145]
	s_waitcnt lgkmcnt(4)
	v_mfma_f32_32x32x16_bf16 v[82:97], v[228:231], v[10:13], v[82:97]
	global_load_dwordx4 v[190:193], v227, s[92:93] offset:1024
	v_mfma_f32_32x32x16_bf16 v[98:113], v[232:235], v[10:13], v[98:113]
	s_waitcnt lgkmcnt(3)
	v_mfma_f32_32x32x16_bf16 v[50:65], v[228:231], v[14:17], v[50:65]
	v_mfma_f32_32x32x16_bf16 v[66:81], v[232:235], v[14:17], v[66:81]
	s_waitcnt lgkmcnt(1)
	v_mfma_f32_32x32x16_bf16 v[18:33], v[228:231], v[236:239], v[18:33]
	v_mfma_f32_32x32x16_bf16 v[34:49], v[232:235], v[236:239], v[34:49]
	s_waitcnt lgkmcnt(0)
	s_barrier
;     ...
;   for (int kt = 0; kt < nk; ++kt) {
;     __syncthreads();
;     if (kt + 1 < nk) {
;       u16* aw = As0 + ((kt + 1) & 1) * 256 * LD;
;       u16* bw = Bs0 + ((kt + 1) & 1) * 256 * LD;
; #pragma unroll
;       for (int i = 0; i < 4; ++i) { *(u32x4*)(aw + (srow + 64 * i) * LD + skc * 8) = ra[i]; *(u32x4*)(bw + (srow + 64 * i) * LD + skc * 8) = rb[i]; }
;     }
;     if (kt + 2 < nk) {
; #pragma unroll
;       for (int i = 0; i < 4; ++i) { ra[i] = *(const u32x4*)(Ag + (size_t)(64 * i) * K + (kt + 2) * 64); rb[i] = *(const u32x4*)(Bg[i] + (kt + 2) * 64); }
;     }
;     __builtin_amdgcn_sched_barrier(0);
;     const u16* as = As0 + (kt & 1) * 256 * LD + (wr * 128 + l31) * LD + h * 8;
;     const u16* bs = Bs0 + (kt & 1) * 256 * LD + (wc * 64 + l31) * LD + h * 8;
;     if (domma)
; #pragma unroll
;     for (int ks = 0; ks < 4; ++ks) {
;       bf16x8 wf[2], xf[4];
; #pragma unroll
;       for (int ct = 0; ct < 2; ++ct) wf[ct] = *(const bf16x8*)(bs + ct * 32 * LD + ks * 16);
; #pragma unroll
;       for (int tt = 0; tt < 4; ++tt) xf[tt] = *(const bf16x8*)(as + tt * 32 * LD + ks * 16);
; #pragma unroll
;       for (int ct = 0; ct < 2; ++ct)
; #pragma unroll
;         for (int tt = 0; tt < 4; ++tt) acc[ct][tt] = __builtin_amdgcn_mfma_f32_32x32x16_bf16(wf[ct], xf[tt], acc[ct][tt], 0, 0, 0);
;     }
	ds_read_b128 v[210:213], v249
	ds_read_b128 v[236:239], v248
	ds_read_b128 v[214:217], v249 offset:4608
	ds_read_b128 v[2:5], v248 offset:4608
	ds_read_b128 v[6:9], v248 offset:9216
	ds_read_b128 v[10:13], v248 offset:13824
	s_waitcnt lgkmcnt(4)
	v_mfma_f32_32x32x16_bf16 v[114:129], v[210:213], v[236:239], v[114:129]
	ds_read_b128 v[228:231], v249 offset:32
	s_waitcnt lgkmcnt(4)
	v_mfma_f32_32x32x16_bf16 v[130:145], v[214:217], v[236:239], v[130:145]
	ds_read_b128 v[14:17], v248 offset:32
	s_waitcnt lgkmcnt(4)
	v_mfma_f32_32x32x16_bf16 v[82:97], v[210:213], v[2:5], v[82:97]
	ds_read_b128 v[232:235], v249 offset:4640
	v_mfma_f32_32x32x16_bf16 v[98:113], v[214:217], v[2:5], v[98:113]
	ds_read_b128 v[236:239], v248 offset:4640
	s_waitcnt vmcnt(15)
	ds_write_b128 v250, v[162:165] offset:36864
	s_waitcnt lgkmcnt(6)
	v_mfma_f32_32x32x16_bf16 v[50:65], v[210:213], v[6:9], v[50:65]
	ds_read_b128 v[2:5], v248 offset:9248
	v_mfma_f32_32x32x16_bf16 v[66:81], v[214:217], v[6:9], v[66:81]
	global_load_dwordx4 v[162:165], v227, s[74:75] offset:1152
	s_waitcnt lgkmcnt(6)
	v_mfma_f32_32x32x16_bf16 v[18:33], v[210:213], v[10:13], v[18:33]
	ds_read_b128 v[6:9], v248 offset:13856
	s_waitcnt vmcnt(15)
	ds_write_b128 v251, v[194:197] offset:36864
	v_mfma_f32_32x32x16_bf16 v[34:49], v[214:217], v[10:13], v[34:49]
	s_waitcnt lgkmcnt(6)
	v_mfma_f32_32x32x16_bf16 v[114:129], v[228:231], v[14:17], v[114:129]
	ds_read_b128 v[210:213], v249 offset:64
	global_load_dwordx4 v[194:197], v227, s[82:83] offset:1152
	s_waitcnt lgkmcnt(6)
	v_mfma_f32_32x32x16_bf16 v[130:145], v[232:235], v[14:17], v[130:145]
	ds_read_b128 v[10:13], v248 offset:64
	s_waitcnt vmcnt(15)
	ds_write_b128 v250, v[166:169] offset:46080
	s_waitcnt lgkmcnt(7)
	v_mfma_f32_32x32x16_bf16 v[82:97], v[228:231], v[236:239], v[82:97]
	ds_read_b128 v[214:217], v249 offset:4672
	v_mfma_f32_32x32x16_bf16 v[98:113], v[232:235], v[236:239], v[98:113]
	ds_read_b128 v[14:17], v248 offset:4672
	global_load_dwordx4 v[166:169], v227, s[76:77] offset:1152
	s_waitcnt lgkmcnt(7)
	v_mfma_f32_32x32x16_bf16 v[50:65], v[228:231], v[2:5], v[50:65]
	ds_read_b128 v[236:239], v248 offset:9280
	s_waitcnt vmcnt(15)
	ds_write_b128 v251, v[198:201] offset:46080
	v_mfma_f32_32x32x16_bf16 v[66:81], v[232:235], v[2:5], v[66:81]
	s_waitcnt lgkmcnt(8)
	v_mfma_f32_32x32x16_bf16 v[18:33], v[228:231], v[6:9], v[18:33]
	ds_read_b128 v[2:5], v248 offset:13888
	global_load_dwordx4 v[198:201], v227, s[84:85] offset:1152
	v_mfma_f32_32x32x16_bf16 v[34:49], v[232:235], v[6:9], v[34:49]
	s_waitcnt vmcnt(15)
	ds_write_b128 v250, v[170:173] offset:55296
	s_waitcnt lgkmcnt(7)
	v_mfma_f32_32x32x16_bf16 v[114:129], v[210:213], v[10:13], v[114:129]
	ds_read_b128 v[228:231], v249 offset:96
	s_waitcnt lgkmcnt(6)
	v_mfma_f32_32x32x16_bf16 v[130:145], v[214:217], v[10:13], v[130:145]
	ds_read_b128 v[6:9], v248 offset:96
	global_load_dwordx4 v[170:173], v227, s[78:79] offset:1152
	s_waitcnt lgkmcnt(6)
	v_mfma_f32_32x32x16_bf16 v[82:97], v[210:213], v[14:17], v[82:97]
	ds_read_b128 v[232:235], v249 offset:4704
	s_waitcnt vmcnt(15)
	ds_write_b128 v251, v[202:205] offset:55296
	v_mfma_f32_32x32x16_bf16 v[98:113], v[214:217], v[14:17], v[98:113]
	ds_read_b128 v[10:13], v248 offset:4704
	s_waitcnt lgkmcnt(8)
	v_mfma_f32_32x32x16_bf16 v[50:65], v[210:213], v[236:239], v[50:65]
	ds_read_b128 v[14:17], v248 offset:9312
	global_load_dwordx4 v[202:205], v227, s[86:87] offset:1152
	v_mfma_f32_32x32x16_bf16 v[66:81], v[214:217], v[236:239], v[66:81]
	s_waitcnt vmcnt(15)
	ds_write_b128 v250, v[174:177] offset:64512
	s_waitcnt lgkmcnt(8)
	v_mfma_f32_32x32x16_bf16 v[18:33], v[210:213], v[2:5], v[18:33]
	ds_read_b128 v[236:239], v248 offset:13920
	v_mfma_f32_32x32x16_bf16 v[34:49], v[214:217], v[2:5], v[34:49]
	global_load_dwordx4 v[174:177], v227, s[80:81] offset:1152
	s_waitcnt lgkmcnt(6)
	v_mfma_f32_32x32x16_bf16 v[114:129], v[228:231], v[6:9], v[114:129]
	s_waitcnt vmcnt(15)
	ds_write_b128 v251, v[206:209] offset:64512
	s_waitcnt lgkmcnt(6)
	v_mfma_f32_32x32x16_bf16 v[130:145], v[232:235], v[6:9], v[130:145]
	s_waitcnt lgkmcnt(4)
	v_mfma_f32_32x32x16_bf16 v[82:97], v[228:231], v[10:13], v[82:97]
	global_load_dwordx4 v[206:209], v227, s[92:93] offset:1152
	v_mfma_f32_32x32x16_bf16 v[98:113], v[232:235], v[10:13], v[98:113]
	s_waitcnt lgkmcnt(3)
	v_mfma_f32_32x32x16_bf16 v[50:65], v[228:231], v[14:17], v[50:65]
	v_mfma_f32_32x32x16_bf16 v[66:81], v[232:235], v[14:17], v[66:81]
	s_waitcnt lgkmcnt(1)
	v_mfma_f32_32x32x16_bf16 v[18:33], v[228:231], v[236:239], v[18:33]
	v_mfma_f32_32x32x16_bf16 v[34:49], v[232:235], v[236:239], v[34:49]
	s_waitcnt lgkmcnt(0)
	s_barrier
;     ...
;   for (int kt = 0; kt < nk; ++kt) {
;     __syncthreads();
;     if (kt + 1 < nk) {
;       u16* aw = As0 + ((kt + 1) & 1) * 256 * LD;
;       u16* bw = Bs0 + ((kt + 1) & 1) * 256 * LD;
; #pragma unroll
;       for (int i = 0; i < 4; ++i) { *(u32x4*)(aw + (srow + 64 * i) * LD + skc * 8) = ra[i]; *(u32x4*)(bw + (srow + 64 * i) * LD + skc * 8) = rb[i]; }
;     }
;     if (kt + 2 < nk) {
; #pragma unroll
;       for (int i = 0; i < 4; ++i) { ra[i] = *(const u32x4*)(Ag + (size_t)(64 * i) * K + (kt + 2) * 64); rb[i] = *(const u32x4*)(Bg[i] + (kt + 2) * 64); }
;     }
;     __builtin_amdgcn_sched_barrier(0);
;     const u16* as = As0 + (kt & 1) * 256 * LD + (wr * 128 + l31) * LD + h * 8;
;     const u16* bs = Bs0 + (kt & 1) * 256 * LD + (wc * 64 + l31) * LD + h * 8;
;     if (domma)
; #pragma unroll
;     for (int ks = 0; ks < 4; ++ks) {
;       bf16x8 wf[2], xf[4];
; #pragma unroll
;       for (int ct = 0; ct < 2; ++ct) wf[ct] = *(const bf16x8*)(bs + ct * 32 * LD + ks * 16);
; #pragma unroll
;       for (int tt = 0; tt < 4; ++tt) xf[tt] = *(const bf16x8*)(as + tt * 32 * LD + ks * 16);
; #pragma unroll
;       for (int ct = 0; ct < 2; ++ct)
; #pragma unroll
;         for (int tt = 0; tt < 4; ++tt) acc[ct][tt] = __builtin_amdgcn_mfma_f32_32x32x16_bf16(wf[ct], xf[tt], acc[ct][tt], 0, 0, 0);
;     }
	ds_read_b128 v[210:213], v249 offset:36864
	ds_read_b128 v[236:239], v248 offset:36864
	ds_read_b128 v[214:217], v249 offset:41472
	ds_read_b128 v[2:5], v248 offset:41472
	ds_read_b128 v[6:9], v248 offset:46080
	ds_read_b128 v[10:13], v248 offset:50688
	s_waitcnt lgkmcnt(4)
	v_mfma_f32_32x32x16_bf16 v[114:129], v[210:213], v[236:239], v[114:129]
	ds_read_b128 v[228:231], v249 offset:36896
	s_waitcnt lgkmcnt(4)
	v_mfma_f32_32x32x16_bf16 v[130:145], v[214:217], v[236:239], v[130:145]
	ds_read_b128 v[14:17], v248 offset:36896
	s_waitcnt lgkmcnt(4)
	v_mfma_f32_32x32x16_bf16 v[82:97], v[210:213], v[2:5], v[82:97]
	ds_read_b128 v[232:235], v249 offset:41504
	v_mfma_f32_32x32x16_bf16 v[98:113], v[214:217], v[2:5], v[98:113]
	ds_read_b128 v[236:239], v248 offset:41504
	s_waitcnt vmcnt(15)
	ds_write_b128 v250, v[146:149]
	s_waitcnt lgkmcnt(6)
	v_mfma_f32_32x32x16_bf16 v[50:65], v[210:213], v[6:9], v[50:65]
	ds_read_b128 v[2:5], v248 offset:46112
	v_mfma_f32_32x32x16_bf16 v[66:81], v[214:217], v[6:9], v[66:81]
	global_load_dwordx4 v[146:149], v227, s[74:75] offset:1280
	s_waitcnt lgkmcnt(6)
	v_mfma_f32_32x32x16_bf16 v[18:33], v[210:213], v[10:13], v[18:33]
	ds_read_b128 v[6:9], v248 offset:50720
	s_waitcnt vmcnt(15)
	ds_write_b128 v251, v[178:181]
	v_mfma_f32_32x32x16_bf16 v[34:49], v[214:217], v[10:13], v[34:49]
	s_waitcnt lgkmcnt(6)
	v_mfma_f32_32x32x16_bf16 v[114:129], v[228:231], v[14:17], v[114:129]
	ds_read_b128 v[210:213], v249 offset:36928
	global_load_dwordx4 v[178:181], v227, s[82:83] offset:1280
	s_waitcnt lgkmcnt(6)
	v_mfma_f32_32x32x16_bf16 v[130:145], v[232:235], v[14:17], v[130:145]
	ds_read_b128 v[10:13], v248 offset:36928
	s_waitcnt vmcnt(15)
	ds_write_b128 v250, v[150:153] offset:9216
	s_waitcnt lgkmcnt(7)
	v_mfma_f32_32x32x16_bf16 v[82:97], v[228:231], v[236:239], v[82:97]
	ds_read_b128 v[214:217], v249 offset:41536
	v_mfma_f32_32x32x16_bf16 v[98:113], v[232:235], v[236:239], v[98:113]
	ds_read_b128 v[14:17], v248 offset:41536
	global_load_dwordx4 v[150:153], v227, s[76:77] offset:1280
	s_waitcnt lgkmcnt(7)
	v_mfma_f32_32x32x16_bf16 v[50:65], v[228:231], v[2:5], v[50:65]
	ds_read_b128 v[236:239], v248 offset:46144
	s_waitcnt vmcnt(15)
	ds_write_b128 v251, v[182:185] offset:9216
	v_mfma_f32_32x32x16_bf16 v[66:81], v[232:235], v[2:5], v[66:81]
	s_waitcnt lgkmcnt(8)
	v_mfma_f32_32x32x16_bf16 v[18:33], v[228:231], v[6:9], v[18:33]
	ds_read_b128 v[2:5], v248 offset:50752
	global_load_dwordx4 v[182:185], v227, s[84:85] offset:1280
	v_mfma_f32_32x32x16_bf16 v[34:49], v[232:235], v[6:9], v[34:49]
	s_waitcnt vmcnt(15)
	ds_write_b128 v250, v[154:157] offset:18432
	s_waitcnt lgkmcnt(7)
	v_mfma_f32_32x32x16_bf16 v[114:129], v[210:213], v[10:13], v[114:129]
	ds_read_b128 v[228:231], v249 offset:36960
	s_waitcnt lgkmcnt(6)
	v_mfma_f32_32x32x16_bf16 v[130:145], v[214:217], v[10:13], v[130:145]
	ds_read_b128 v[6:9], v248 offset:36960
	global_load_dwordx4 v[154:157], v227, s[78:79] offset:1280
	s_waitcnt lgkmcnt(6)
	v_mfma_f32_32x32x16_bf16 v[82:97], v[210:213], v[14:17], v[82:97]
	ds_read_b128 v[232:235], v249 offset:41568
	s_waitcnt vmcnt(15)
	ds_write_b128 v251, v[186:189] offset:18432
	v_mfma_f32_32x32x16_bf16 v[98:113], v[214:217], v[14:17], v[98:113]
	ds_read_b128 v[10:13], v248 offset:41568
	s_waitcnt lgkmcnt(8)
	v_mfma_f32_32x32x16_bf16 v[50:65], v[210:213], v[236:239], v[50:65]
	ds_read_b128 v[14:17], v248 offset:46176
	global_load_dwordx4 v[186:189], v227, s[86:87] offset:1280
	v_mfma_f32_32x32x16_bf16 v[66:81], v[214:217], v[236:239], v[66:81]
	s_waitcnt vmcnt(15)
	ds_write_b128 v250, v[158:161] offset:27648
	s_waitcnt lgkmcnt(8)
	v_mfma_f32_32x32x16_bf16 v[18:33], v[210:213], v[2:5], v[18:33]
	ds_read_b128 v[236:239], v248 offset:50784
	v_mfma_f32_32x32x16_bf16 v[34:49], v[214:217], v[2:5], v[34:49]
	global_load_dwordx4 v[158:161], v227, s[80:81] offset:1280
	s_waitcnt lgkmcnt(6)
	v_mfma_f32_32x32x16_bf16 v[114:129], v[228:231], v[6:9], v[114:129]
	s_waitcnt vmcnt(15)
	ds_write_b128 v251, v[190:193] offset:27648
	s_waitcnt lgkmcnt(6)
	v_mfma_f32_32x32x16_bf16 v[130:145], v[232:235], v[6:9], v[130:145]
	s_waitcnt lgkmcnt(4)
	v_mfma_f32_32x32x16_bf16 v[82:97], v[228:231], v[10:13], v[82:97]
	global_load_dwordx4 v[190:193], v227, s[92:93] offset:1280
	v_mfma_f32_32x32x16_bf16 v[98:113], v[232:235], v[10:13], v[98:113]
	s_waitcnt lgkmcnt(3)
	v_mfma_f32_32x32x16_bf16 v[50:65], v[228:231], v[14:17], v[50:65]
	v_mfma_f32_32x32x16_bf16 v[66:81], v[232:235], v[14:17], v[66:81]
	s_waitcnt lgkmcnt(1)
	v_mfma_f32_32x32x16_bf16 v[18:33], v[228:231], v[236:239], v[18:33]
	v_mfma_f32_32x32x16_bf16 v[34:49], v[232:235], v[236:239], v[34:49]
	s_waitcnt lgkmcnt(0)
	s_barrier
;     ...
;   for (int kt = 0; kt < nk; ++kt) {
;     __syncthreads();
;     if (kt + 1 < nk) {
;       u16* aw = As0 + ((kt + 1) & 1) * 256 * LD;
;       u16* bw = Bs0 + ((kt + 1) & 1) * 256 * LD;
; #pragma unroll
;       for (int i = 0; i < 4; ++i) { *(u32x4*)(aw + (srow + 64 * i) * LD + skc * 8) = ra[i]; *(u32x4*)(bw + (srow + 64 * i) * LD + skc * 8) = rb[i]; }
;     }
;     if (kt + 2 < nk) {
; #pragma unroll
;       for (int i = 0; i < 4; ++i) { ra[i] = *(const u32x4*)(Ag + (size_t)(64 * i) * K + (kt + 2) * 64); rb[i] = *(const u32x4*)(Bg[i] + (kt + 2) * 64); }
;     }
;     __builtin_amdgcn_sched_barrier(0);
;     const u16* as = As0 + (kt & 1) * 256 * LD + (wr * 128 + l31) * LD + h * 8;
;     const u16* bs = Bs0 + (kt & 1) * 256 * LD + (wc * 64 + l31) * LD + h * 8;
;     if (domma)
; #pragma unroll
;     for (int ks = 0; ks < 4; ++ks) {
;       bf16x8 wf[2], xf[4];
; #pragma unroll
;       for (int ct = 0; ct < 2; ++ct) wf[ct] = *(const bf16x8*)(bs + ct * 32 * LD + ks * 16);
; #pragma unroll
;       for (int tt = 0; tt < 4; ++tt) xf[tt] = *(const bf16x8*)(as + tt * 32 * LD + ks * 16);
; #pragma unroll
;       for (int ct = 0; ct < 2; ++ct)
; #pragma unroll
;         for (int tt = 0; tt < 4; ++tt) acc[ct][tt] = __builtin_amdgcn_mfma_f32_32x32x16_bf16(wf[ct], xf[tt], acc[ct][tt], 0, 0, 0);
;     }
	ds_read_b128 v[210:213], v249
	ds_read_b128 v[236:239], v248
	ds_read_b128 v[214:217], v249 offset:4608
	ds_read_b128 v[2:5], v248 offset:4608
	ds_read_b128 v[6:9], v248 offset:9216
	ds_read_b128 v[10:13], v248 offset:13824
	s_waitcnt lgkmcnt(4)
	v_mfma_f32_32x32x16_bf16 v[114:129], v[210:213], v[236:239], v[114:129]
	ds_read_b128 v[228:231], v249 offset:32
	s_waitcnt lgkmcnt(4)
	v_mfma_f32_32x32x16_bf16 v[130:145], v[214:217], v[236:239], v[130:145]
	ds_read_b128 v[14:17], v248 offset:32
	s_waitcnt lgkmcnt(4)
	v_mfma_f32_32x32x16_bf16 v[82:97], v[210:213], v[2:5], v[82:97]
	ds_read_b128 v[232:235], v249 offset:4640
	v_mfma_f32_32x32x16_bf16 v[98:113], v[214:217], v[2:5], v[98:113]
	ds_read_b128 v[236:239], v248 offset:4640
	s_waitcnt vmcnt(15)
	ds_write_b128 v250, v[162:165] offset:36864
	s_waitcnt lgkmcnt(6)
	v_mfma_f32_32x32x16_bf16 v[50:65], v[210:213], v[6:9], v[50:65]
	ds_read_b128 v[2:5], v248 offset:9248
	v_mfma_f32_32x32x16_bf16 v[66:81], v[214:217], v[6:9], v[66:81]
	global_load_dwordx4 v[162:165], v227, s[74:75] offset:1408
	s_waitcnt lgkmcnt(6)
	v_mfma_f32_32x32x16_bf16 v[18:33], v[210:213], v[10:13], v[18:33]
	ds_read_b128 v[6:9], v248 offset:13856
	s_waitcnt vmcnt(15)
	ds_write_b128 v251, v[194:197] offset:36864
	v_mfma_f32_32x32x16_bf16 v[34:49], v[214:217], v[10:13], v[34:49]
	s_waitcnt lgkmcnt(6)
	v_mfma_f32_32x32x16_bf16 v[114:129], v[228:231], v[14:17], v[114:129]
	ds_read_b128 v[210:213], v249 offset:64
	global_load_dwordx4 v[194:197], v227, s[82:83] offset:1408
	s_waitcnt lgkmcnt(6)
	v_mfma_f32_32x32x16_bf16 v[130:145], v[232:235], v[14:17], v[130:145]
	ds_read_b128 v[10:13], v248 offset:64
	s_waitcnt vmcnt(15)
	ds_write_b128 v250, v[166:169] offset:46080
	s_waitcnt lgkmcnt(7)
	v_mfma_f32_32x32x16_bf16 v[82:97], v[228:231], v[236:239], v[82:97]
	ds_read_b128 v[214:217], v249 offset:4672
	v_mfma_f32_32x32x16_bf16 v[98:113], v[232:235], v[236:239], v[98:113]
	ds_read_b128 v[14:17], v248 offset:4672
	global_load_dwordx4 v[166:169], v227, s[76:77] offset:1408
	s_waitcnt lgkmcnt(7)
	v_mfma_f32_32x32x16_bf16 v[50:65], v[228:231], v[2:5], v[50:65]
	ds_read_b128 v[236:239], v248 offset:9280
	s_waitcnt vmcnt(15)
	ds_write_b128 v251, v[198:201] offset:46080
	v_mfma_f32_32x32x16_bf16 v[66:81], v[232:235], v[2:5], v[66:81]
	s_waitcnt lgkmcnt(8)
	v_mfma_f32_32x32x16_bf16 v[18:33], v[228:231], v[6:9], v[18:33]
	ds_read_b128 v[2:5], v248 offset:13888
	global_load_dwordx4 v[198:201], v227, s[84:85] offset:1408
	v_mfma_f32_32x32x16_bf16 v[34:49], v[232:235], v[6:9], v[34:49]
	s_waitcnt vmcnt(15)
	ds_write_b128 v250, v[170:173] offset:55296
	s_waitcnt lgkmcnt(7)
	v_mfma_f32_32x32x16_bf16 v[114:129], v[210:213], v[10:13], v[114:129]
	ds_read_b128 v[228:231], v249 offset:96
	s_waitcnt lgkmcnt(6)
	v_mfma_f32_32x32x16_bf16 v[130:145], v[214:217], v[10:13], v[130:145]
	ds_read_b128 v[6:9], v248 offset:96
	global_load_dwordx4 v[170:173], v227, s[78:79] offset:1408
	s_waitcnt lgkmcnt(6)
	v_mfma_f32_32x32x16_bf16 v[82:97], v[210:213], v[14:17], v[82:97]
	ds_read_b128 v[232:235], v249 offset:4704
	s_waitcnt vmcnt(15)
	ds_write_b128 v251, v[202:205] offset:55296
	v_mfma_f32_32x32x16_bf16 v[98:113], v[214:217], v[14:17], v[98:113]
	ds_read_b128 v[10:13], v248 offset:4704
	s_waitcnt lgkmcnt(8)
	v_mfma_f32_32x32x16_bf16 v[50:65], v[210:213], v[236:239], v[50:65]
	ds_read_b128 v[14:17], v248 offset:9312
	global_load_dwordx4 v[202:205], v227, s[86:87] offset:1408
	v_mfma_f32_32x32x16_bf16 v[66:81], v[214:217], v[236:239], v[66:81]
	s_waitcnt vmcnt(15)
	ds_write_b128 v250, v[174:177] offset:64512
	s_waitcnt lgkmcnt(8)
	v_mfma_f32_32x32x16_bf16 v[18:33], v[210:213], v[2:5], v[18:33]
	ds_read_b128 v[236:239], v248 offset:13920
	v_mfma_f32_32x32x16_bf16 v[34:49], v[214:217], v[2:5], v[34:49]
	global_load_dwordx4 v[174:177], v227, s[80:81] offset:1408
	s_waitcnt lgkmcnt(6)
	v_mfma_f32_32x32x16_bf16 v[114:129], v[228:231], v[6:9], v[114:129]
	s_waitcnt vmcnt(15)
	ds_write_b128 v251, v[206:209] offset:64512
	s_waitcnt lgkmcnt(6)
	v_mfma_f32_32x32x16_bf16 v[130:145], v[232:235], v[6:9], v[130:145]
	s_waitcnt lgkmcnt(4)
	v_mfma_f32_32x32x16_bf16 v[82:97], v[228:231], v[10:13], v[82:97]
	global_load_dwordx4 v[206:209], v227, s[92:93] offset:1408
	v_mfma_f32_32x32x16_bf16 v[98:113], v[232:235], v[10:13], v[98:113]
	s_waitcnt lgkmcnt(3)
	v_mfma_f32_32x32x16_bf16 v[50:65], v[228:231], v[14:17], v[50:65]
	v_mfma_f32_32x32x16_bf16 v[66:81], v[232:235], v[14:17], v[66:81]
	s_waitcnt lgkmcnt(1)
	v_mfma_f32_32x32x16_bf16 v[18:33], v[228:231], v[236:239], v[18:33]
	v_mfma_f32_32x32x16_bf16 v[34:49], v[232:235], v[236:239], v[34:49]
	s_waitcnt lgkmcnt(0)
	s_barrier
;     ...
;   for (int kt = 0; kt < nk; ++kt) {
;     __syncthreads();
;     if (kt + 1 < nk) {
;       u16* aw = As0 + ((kt + 1) & 1) * 256 * LD;
;       u16* bw = Bs0 + ((kt + 1) & 1) * 256 * LD;
; #pragma unroll
;       for (int i = 0; i < 4; ++i) { *(u32x4*)(aw + (srow + 64 * i) * LD + skc * 8) = ra[i]; *(u32x4*)(bw + (srow + 64 * i) * LD + skc * 8) = rb[i]; }
;     }
;     if (kt + 2 < nk) {
; #pragma unroll
;       for (int i = 0; i < 4; ++i) { ra[i] = *(const u32x4*)(Ag + (size_t)(64 * i) * K + (kt + 2) * 64); rb[i] = *(const u32x4*)(Bg[i] + (kt + 2) * 64); }
;     }
;     __builtin_amdgcn_sched_barrier(0);
;     const u16* as = As0 + (kt & 1) * 256 * LD + (wr * 128 + l31) * LD + h * 8;
;     const u16* bs = Bs0 + (kt & 1) * 256 * LD + (wc * 64 + l31) * LD + h * 8;
;     if (domma)
; #pragma unroll
;     for (int ks = 0; ks < 4; ++ks) {
;       bf16x8 wf[2], xf[4];
; #pragma unroll
;       for (int ct = 0; ct < 2; ++ct) wf[ct] = *(const bf16x8*)(bs + ct * 32 * LD + ks * 16);
; #pragma unroll
;       for (int tt = 0; tt < 4; ++tt) xf[tt] = *(const bf16x8*)(as + tt * 32 * LD + ks * 16);
; #pragma unroll
;       for (int ct = 0; ct < 2; ++ct)
; #pragma unroll
;         for (int tt = 0; tt < 4; ++tt) acc[ct][tt] = __builtin_amdgcn_mfma_f32_32x32x16_bf16(wf[ct], xf[tt], acc[ct][tt], 0, 0, 0);
;     }
	ds_read_b128 v[210:213], v249 offset:36864
	ds_read_b128 v[236:239], v248 offset:36864
	ds_read_b128 v[214:217], v249 offset:41472
	ds_read_b128 v[2:5], v248 offset:41472
	ds_read_b128 v[6:9], v248 offset:46080
	ds_read_b128 v[10:13], v248 offset:50688
	s_waitcnt lgkmcnt(4)
	v_mfma_f32_32x32x16_bf16 v[114:129], v[210:213], v[236:239], v[114:129]
	ds_read_b128 v[228:231], v249 offset:36896
	s_waitcnt lgkmcnt(4)
	v_mfma_f32_32x32x16_bf16 v[130:145], v[214:217], v[236:239], v[130:145]
	ds_read_b128 v[14:17], v248 offset:36896
	s_waitcnt lgkmcnt(4)
	v_mfma_f32_32x32x16_bf16 v[82:97], v[210:213], v[2:5], v[82:97]
	ds_read_b128 v[232:235], v249 offset:41504
	v_mfma_f32_32x32x16_bf16 v[98:113], v[214:217], v[2:5], v[98:113]
	ds_read_b128 v[236:239], v248 offset:41504
	s_waitcnt vmcnt(15)
	ds_write_b128 v250, v[146:149]
	s_waitcnt lgkmcnt(6)
	v_mfma_f32_32x32x16_bf16 v[50:65], v[210:213], v[6:9], v[50:65]
	ds_read_b128 v[2:5], v248 offset:46112
	v_mfma_f32_32x32x16_bf16 v[66:81], v[214:217], v[6:9], v[66:81]
	global_load_dwordx4 v[146:149], v227, s[74:75] offset:1536
	s_waitcnt lgkmcnt(6)
	v_mfma_f32_32x32x16_bf16 v[18:33], v[210:213], v[10:13], v[18:33]
	ds_read_b128 v[6:9], v248 offset:50720
	s_waitcnt vmcnt(15)
	ds_write_b128 v251, v[178:181]
	v_mfma_f32_32x32x16_bf16 v[34:49], v[214:217], v[10:13], v[34:49]
	s_waitcnt lgkmcnt(6)
	v_mfma_f32_32x32x16_bf16 v[114:129], v[228:231], v[14:17], v[114:129]
	ds_read_b128 v[210:213], v249 offset:36928
	global_load_dwordx4 v[178:181], v227, s[82:83] offset:1536
	s_waitcnt lgkmcnt(6)
	v_mfma_f32_32x32x16_bf16 v[130:145], v[232:235], v[14:17], v[130:145]
	ds_read_b128 v[10:13], v248 offset:36928
	s_waitcnt vmcnt(15)
	ds_write_b128 v250, v[150:153] offset:9216
	s_waitcnt lgkmcnt(7)
	v_mfma_f32_32x32x16_bf16 v[82:97], v[228:231], v[236:239], v[82:97]
	ds_read_b128 v[214:217], v249 offset:41536
	v_mfma_f32_32x32x16_bf16 v[98:113], v[232:235], v[236:239], v[98:113]
	ds_read_b128 v[14:17], v248 offset:41536
	global_load_dwordx4 v[150:153], v227, s[76:77] offset:1536
	s_waitcnt lgkmcnt(7)
	v_mfma_f32_32x32x16_bf16 v[50:65], v[228:231], v[2:5], v[50:65]
	ds_read_b128 v[236:239], v248 offset:46144
	s_waitcnt vmcnt(15)
	ds_write_b128 v251, v[182:185] offset:9216
	v_mfma_f32_32x32x16_bf16 v[66:81], v[232:235], v[2:5], v[66:81]
	s_waitcnt lgkmcnt(8)
	v_mfma_f32_32x32x16_bf16 v[18:33], v[228:231], v[6:9], v[18:33]
	ds_read_b128 v[2:5], v248 offset:50752
	global_load_dwordx4 v[182:185], v227, s[84:85] offset:1536
	v_mfma_f32_32x32x16_bf16 v[34:49], v[232:235], v[6:9], v[34:49]
	s_waitcnt vmcnt(15)
	ds_write_b128 v250, v[154:157] offset:18432
	s_waitcnt lgkmcnt(7)
	v_mfma_f32_32x32x16_bf16 v[114:129], v[210:213], v[10:13], v[114:129]
	ds_read_b128 v[228:231], v249 offset:36960
	s_waitcnt lgkmcnt(6)
	v_mfma_f32_32x32x16_bf16 v[130:145], v[214:217], v[10:13], v[130:145]
	ds_read_b128 v[6:9], v248 offset:36960
	global_load_dwordx4 v[154:157], v227, s[78:79] offset:1536
	s_waitcnt lgkmcnt(6)
	v_mfma_f32_32x32x16_bf16 v[82:97], v[210:213], v[14:17], v[82:97]
	ds_read_b128 v[232:235], v249 offset:41568
	s_waitcnt vmcnt(15)
	ds_write_b128 v251, v[186:189] offset:18432
	v_mfma_f32_32x32x16_bf16 v[98:113], v[214:217], v[14:17], v[98:113]
	ds_read_b128 v[10:13], v248 offset:41568
	s_waitcnt lgkmcnt(8)
	v_mfma_f32_32x32x16_bf16 v[50:65], v[210:213], v[236:239], v[50:65]
	ds_read_b128 v[14:17], v248 offset:46176
	global_load_dwordx4 v[186:189], v227, s[86:87] offset:1536
	v_mfma_f32_32x32x16_bf16 v[66:81], v[214:217], v[236:239], v[66:81]
	s_waitcnt vmcnt(15)
	ds_write_b128 v250, v[158:161] offset:27648
	s_waitcnt lgkmcnt(8)
	v_mfma_f32_32x32x16_bf16 v[18:33], v[210:213], v[2:5], v[18:33]
	ds_read_b128 v[236:239], v248 offset:50784
	v_mfma_f32_32x32x16_bf16 v[34:49], v[214:217], v[2:5], v[34:49]
	global_load_dwordx4 v[158:161], v227, s[80:81] offset:1536
	s_waitcnt lgkmcnt(6)
	v_mfma_f32_32x32x16_bf16 v[114:129], v[228:231], v[6:9], v[114:129]
	s_waitcnt vmcnt(15)
	ds_write_b128 v251, v[190:193] offset:27648
	s_waitcnt lgkmcnt(6)
	v_mfma_f32_32x32x16_bf16 v[130:145], v[232:235], v[6:9], v[130:145]
	s_waitcnt lgkmcnt(4)
	v_mfma_f32_32x32x16_bf16 v[82:97], v[228:231], v[10:13], v[82:97]
	global_load_dwordx4 v[190:193], v227, s[92:93] offset:1536
	v_mfma_f32_32x32x16_bf16 v[98:113], v[232:235], v[10:13], v[98:113]
	s_waitcnt lgkmcnt(3)
	v_mfma_f32_32x32x16_bf16 v[50:65], v[228:231], v[14:17], v[50:65]
	v_mfma_f32_32x32x16_bf16 v[66:81], v[232:235], v[14:17], v[66:81]
	s_waitcnt lgkmcnt(1)
	v_mfma_f32_32x32x16_bf16 v[18:33], v[228:231], v[236:239], v[18:33]
	v_mfma_f32_32x32x16_bf16 v[34:49], v[232:235], v[236:239], v[34:49]
	s_waitcnt lgkmcnt(0)
	s_barrier
;     ...
;   for (int kt = 0; kt < nk; ++kt) {
;     __syncthreads();
;     if (kt + 1 < nk) {
;       u16* aw = As0 + ((kt + 1) & 1) * 256 * LD;
;       u16* bw = Bs0 + ((kt + 1) & 1) * 256 * LD;
; #pragma unroll
;       for (int i = 0; i < 4; ++i) { *(u32x4*)(aw + (srow + 64 * i) * LD + skc * 8) = ra[i]; *(u32x4*)(bw + (srow + 64 * i) * LD + skc * 8) = rb[i]; }
;     }
;     if (kt + 2 < nk) {
; #pragma unroll
;       for (int i = 0; i < 4; ++i) { ra[i] = *(const u32x4*)(Ag + (size_t)(64 * i) * K + (kt + 2) * 64); rb[i] = *(const u32x4*)(Bg[i] + (kt + 2) * 64); }
;     }
;     __builtin_amdgcn_sched_barrier(0);
;     const u16* as = As0 + (kt & 1) * 256 * LD + (wr * 128 + l31) * LD + h * 8;
;     const u16* bs = Bs0 + (kt & 1) * 256 * LD + (wc * 64 + l31) * LD + h * 8;
;     if (domma)
; #pragma unroll
;     for (int ks = 0; ks < 4; ++ks) {
;       bf16x8 wf[2], xf[4];
; #pragma unroll
;       for (int ct = 0; ct < 2; ++ct) wf[ct] = *(const bf16x8*)(bs + ct * 32 * LD + ks * 16);
; #pragma unroll
;       for (int tt = 0; tt < 4; ++tt) xf[tt] = *(const bf16x8*)(as + tt * 32 * LD + ks * 16);
; #pragma unroll
;       for (int ct = 0; ct < 2; ++ct)
; #pragma unroll
;         for (int tt = 0; tt < 4; ++tt) acc[ct][tt] = __builtin_amdgcn_mfma_f32_32x32x16_bf16(wf[ct], xf[tt], acc[ct][tt], 0, 0, 0);
;     }
	ds_read_b128 v[210:213], v249
	ds_read_b128 v[236:239], v248
	ds_read_b128 v[214:217], v249 offset:4608
	ds_read_b128 v[2:5], v248 offset:4608
	ds_read_b128 v[6:9], v248 offset:9216
	ds_read_b128 v[10:13], v248 offset:13824
	s_waitcnt lgkmcnt(4)
	v_mfma_f32_32x32x16_bf16 v[114:129], v[210:213], v[236:239], v[114:129]
	ds_read_b128 v[228:231], v249 offset:32
	s_waitcnt lgkmcnt(4)
	v_mfma_f32_32x32x16_bf16 v[130:145], v[214:217], v[236:239], v[130:145]
	ds_read_b128 v[14:17], v248 offset:32
	s_waitcnt lgkmcnt(4)
	v_mfma_f32_32x32x16_bf16 v[82:97], v[210:213], v[2:5], v[82:97]
	ds_read_b128 v[232:235], v249 offset:4640
	v_mfma_f32_32x32x16_bf16 v[98:113], v[214:217], v[2:5], v[98:113]
	ds_read_b128 v[236:239], v248 offset:4640
	s_waitcnt vmcnt(15)
	ds_write_b128 v250, v[162:165] offset:36864
	s_waitcnt lgkmcnt(6)
	v_mfma_f32_32x32x16_bf16 v[50:65], v[210:213], v[6:9], v[50:65]
	ds_read_b128 v[2:5], v248 offset:9248
	v_mfma_f32_32x32x16_bf16 v[66:81], v[214:217], v[6:9], v[66:81]
	global_load_dwordx4 v[162:165], v227, s[74:75] offset:1664
	s_waitcnt lgkmcnt(6)
	v_mfma_f32_32x32x16_bf16 v[18:33], v[210:213], v[10:13], v[18:33]
	ds_read_b128 v[6:9], v248 offset:13856
	s_waitcnt vmcnt(15)
	ds_write_b128 v251, v[194:197] offset:36864
	v_mfma_f32_32x32x16_bf16 v[34:49], v[214:217], v[10:13], v[34:49]
	s_waitcnt lgkmcnt(6)
	v_mfma_f32_32x32x16_bf16 v[114:129], v[228:231], v[14:17], v[114:129]
	ds_read_b128 v[210:213], v249 offset:64
	global_load_dwordx4 v[194:197], v227, s[82:83] offset:1664
	s_waitcnt lgkmcnt(6)
	v_mfma_f32_32x32x16_bf16 v[130:145], v[232:235], v[14:17], v[130:145]
	ds_read_b128 v[10:13], v248 offset:64
	s_waitcnt vmcnt(15)
	ds_write_b128 v250, v[166:169] offset:46080
	s_waitcnt lgkmcnt(7)
	v_mfma_f32_32x32x16_bf16 v[82:97], v[228:231], v[236:239], v[82:97]
	ds_read_b128 v[214:217], v249 offset:4672
	v_mfma_f32_32x32x16_bf16 v[98:113], v[232:235], v[236:239], v[98:113]
	ds_read_b128 v[14:17], v248 offset:4672
	global_load_dwordx4 v[166:169], v227, s[76:77] offset:1664
	s_waitcnt lgkmcnt(7)
	v_mfma_f32_32x32x16_bf16 v[50:65], v[228:231], v[2:5], v[50:65]
	ds_read_b128 v[236:239], v248 offset:9280
	s_waitcnt vmcnt(15)
	ds_write_b128 v251, v[198:201] offset:46080
	v_mfma_f32_32x32x16_bf16 v[66:81], v[232:235], v[2:5], v[66:81]
	s_waitcnt lgkmcnt(8)
	v_mfma_f32_32x32x16_bf16 v[18:33], v[228:231], v[6:9], v[18:33]
	ds_read_b128 v[2:5], v248 offset:13888
	global_load_dwordx4 v[198:201], v227, s[84:85] offset:1664
	v_mfma_f32_32x32x16_bf16 v[34:49], v[232:235], v[6:9], v[34:49]
	s_waitcnt vmcnt(15)
	ds_write_b128 v250, v[170:173] offset:55296
	s_waitcnt lgkmcnt(7)
	v_mfma_f32_32x32x16_bf16 v[114:129], v[210:213], v[10:13], v[114:129]
	ds_read_b128 v[228:231], v249 offset:96
	s_waitcnt lgkmcnt(6)
	v_mfma_f32_32x32x16_bf16 v[130:145], v[214:217], v[10:13], v[130:145]
	ds_read_b128 v[6:9], v248 offset:96
	global_load_dwordx4 v[170:173], v227, s[78:79] offset:1664
	s_waitcnt lgkmcnt(6)
	v_mfma_f32_32x32x16_bf16 v[82:97], v[210:213], v[14:17], v[82:97]
	ds_read_b128 v[232:235], v249 offset:4704
	s_waitcnt vmcnt(15)
	ds_write_b128 v251, v[202:205] offset:55296
	v_mfma_f32_32x32x16_bf16 v[98:113], v[214:217], v[14:17], v[98:113]
	ds_read_b128 v[10:13], v248 offset:4704
	s_waitcnt lgkmcnt(8)
	v_mfma_f32_32x32x16_bf16 v[50:65], v[210:213], v[236:239], v[50:65]
	ds_read_b128 v[14:17], v248 offset:9312
	global_load_dwordx4 v[202:205], v227, s[86:87] offset:1664
	v_mfma_f32_32x32x16_bf16 v[66:81], v[214:217], v[236:239], v[66:81]
	s_waitcnt vmcnt(15)
	ds_write_b128 v250, v[174:177] offset:64512
	s_waitcnt lgkmcnt(8)
	v_mfma_f32_32x32x16_bf16 v[18:33], v[210:213], v[2:5], v[18:33]
	ds_read_b128 v[236:239], v248 offset:13920
	v_mfma_f32_32x32x16_bf16 v[34:49], v[214:217], v[2:5], v[34:49]
	global_load_dwordx4 v[174:177], v227, s[80:81] offset:1664
	s_waitcnt lgkmcnt(6)
	v_mfma_f32_32x32x16_bf16 v[114:129], v[228:231], v[6:9], v[114:129]
	s_waitcnt vmcnt(15)
	ds_write_b128 v251, v[206:209] offset:64512
	s_waitcnt lgkmcnt(6)
	v_mfma_f32_32x32x16_bf16 v[130:145], v[232:235], v[6:9], v[130:145]
	s_waitcnt lgkmcnt(4)
	v_mfma_f32_32x32x16_bf16 v[82:97], v[228:231], v[10:13], v[82:97]
	global_load_dwordx4 v[206:209], v227, s[92:93] offset:1664
	v_mfma_f32_32x32x16_bf16 v[98:113], v[232:235], v[10:13], v[98:113]
	s_waitcnt lgkmcnt(3)
	v_mfma_f32_32x32x16_bf16 v[50:65], v[228:231], v[14:17], v[50:65]
	v_mfma_f32_32x32x16_bf16 v[66:81], v[232:235], v[14:17], v[66:81]
	s_waitcnt lgkmcnt(1)
	v_mfma_f32_32x32x16_bf16 v[18:33], v[228:231], v[236:239], v[18:33]
	v_mfma_f32_32x32x16_bf16 v[34:49], v[232:235], v[236:239], v[34:49]
	s_waitcnt lgkmcnt(0)
	s_barrier
;     ...
;   for (int kt = 0; kt < nk; ++kt) {
;     __syncthreads();
;     if (kt + 1 < nk) {
;       u16* aw = As0 + ((kt + 1) & 1) * 256 * LD;
;       u16* bw = Bs0 + ((kt + 1) & 1) * 256 * LD;
; #pragma unroll
;       for (int i = 0; i < 4; ++i) { *(u32x4*)(aw + (srow + 64 * i) * LD + skc * 8) = ra[i]; *(u32x4*)(bw + (srow + 64 * i) * LD + skc * 8) = rb[i]; }
;     }
;     if (kt + 2 < nk) {
; #pragma unroll
;       for (int i = 0; i < 4; ++i) { ra[i] = *(const u32x4*)(Ag + (size_t)(64 * i) * K + (kt + 2) * 64); rb[i] = *(const u32x4*)(Bg[i] + (kt + 2) * 64); }
;     }
;     __builtin_amdgcn_sched_barrier(0);
;     const u16* as = As0 + (kt & 1) * 256 * LD + (wr * 128 + l31) * LD + h * 8;
;     const u16* bs = Bs0 + (kt & 1) * 256 * LD + (wc * 64 + l31) * LD + h * 8;
;     if (domma)
; #pragma unroll
;     for (int ks = 0; ks < 4; ++ks) {
;       bf16x8 wf[2], xf[4];
; #pragma unroll
;       for (int ct = 0; ct < 2; ++ct) wf[ct] = *(const bf16x8*)(bs + ct * 32 * LD + ks * 16);
; #pragma unroll
;       for (int tt = 0; tt < 4; ++tt) xf[tt] = *(const bf16x8*)(as + tt * 32 * LD + ks * 16);
; #pragma unroll
;       for (int ct = 0; ct < 2; ++ct)
; #pragma unroll
;         for (int tt = 0; tt < 4; ++tt) acc[ct][tt] = __builtin_amdgcn_mfma_f32_32x32x16_bf16(wf[ct], xf[tt], acc[ct][tt], 0, 0, 0);
;     }
	ds_read_b128 v[210:213], v249 offset:36864
	ds_read_b128 v[236:239], v248 offset:36864
	ds_read_b128 v[214:217], v249 offset:41472
	ds_read_b128 v[2:5], v248 offset:41472
	ds_read_b128 v[6:9], v248 offset:46080
	ds_read_b128 v[10:13], v248 offset:50688
	s_waitcnt lgkmcnt(4)
	v_mfma_f32_32x32x16_bf16 v[114:129], v[210:213], v[236:239], v[114:129]
	ds_read_b128 v[228:231], v249 offset:36896
	s_waitcnt lgkmcnt(4)
	v_mfma_f32_32x32x16_bf16 v[130:145], v[214:217], v[236:239], v[130:145]
	ds_read_b128 v[14:17], v248 offset:36896
	s_waitcnt lgkmcnt(4)
	v_mfma_f32_32x32x16_bf16 v[82:97], v[210:213], v[2:5], v[82:97]
	ds_read_b128 v[232:235], v249 offset:41504
	v_mfma_f32_32x32x16_bf16 v[98:113], v[214:217], v[2:5], v[98:113]
	ds_read_b128 v[236:239], v248 offset:41504
	s_waitcnt vmcnt(15)
	ds_write_b128 v250, v[146:149]
	s_waitcnt lgkmcnt(6)
	v_mfma_f32_32x32x16_bf16 v[50:65], v[210:213], v[6:9], v[50:65]
	ds_read_b128 v[2:5], v248 offset:46112
	v_mfma_f32_32x32x16_bf16 v[66:81], v[214:217], v[6:9], v[66:81]
	global_load_dwordx4 v[146:149], v227, s[74:75] offset:1792
	s_waitcnt lgkmcnt(6)
	v_mfma_f32_32x32x16_bf16 v[18:33], v[210:213], v[10:13], v[18:33]
	ds_read_b128 v[6:9], v248 offset:50720
	s_waitcnt vmcnt(15)
	ds_write_b128 v251, v[178:181]
	v_mfma_f32_32x32x16_bf16 v[34:49], v[214:217], v[10:13], v[34:49]
	s_waitcnt lgkmcnt(6)
	v_mfma_f32_32x32x16_bf16 v[114:129], v[228:231], v[14:17], v[114:129]
	ds_read_b128 v[210:213], v249 offset:36928
	global_load_dwordx4 v[178:181], v227, s[82:83] offset:1792
	s_waitcnt lgkmcnt(6)
	v_mfma_f32_32x32x16_bf16 v[130:145], v[232:235], v[14:17], v[130:145]
	ds_read_b128 v[10:13], v248 offset:36928
	s_waitcnt vmcnt(15)
	ds_write_b128 v250, v[150:153] offset:9216
	s_waitcnt lgkmcnt(7)
	v_mfma_f32_32x32x16_bf16 v[82:97], v[228:231], v[236:239], v[82:97]
	ds_read_b128 v[214:217], v249 offset:41536
	v_mfma_f32_32x32x16_bf16 v[98:113], v[232:235], v[236:239], v[98:113]
	ds_read_b128 v[14:17], v248 offset:41536
	global_load_dwordx4 v[150:153], v227, s[76:77] offset:1792
	s_waitcnt lgkmcnt(7)
	v_mfma_f32_32x32x16_bf16 v[50:65], v[228:231], v[2:5], v[50:65]
	ds_read_b128 v[236:239], v248 offset:46144
	s_waitcnt vmcnt(15)
	ds_write_b128 v251, v[182:185] offset:9216
	v_mfma_f32_32x32x16_bf16 v[66:81], v[232:235], v[2:5], v[66:81]
	s_waitcnt lgkmcnt(8)
	v_mfma_f32_32x32x16_bf16 v[18:33], v[228:231], v[6:9], v[18:33]
	ds_read_b128 v[2:5], v248 offset:50752
	global_load_dwordx4 v[182:185], v227, s[84:85] offset:1792
	v_mfma_f32_32x32x16_bf16 v[34:49], v[232:235], v[6:9], v[34:49]
	s_waitcnt vmcnt(15)
	ds_write_b128 v250, v[154:157] offset:18432
	s_waitcnt lgkmcnt(7)
	v_mfma_f32_32x32x16_bf16 v[114:129], v[210:213], v[10:13], v[114:129]
	ds_read_b128 v[228:231], v249 offset:36960
	s_waitcnt lgkmcnt(6)
	v_mfma_f32_32x32x16_bf16 v[130:145], v[214:217], v[10:13], v[130:145]
	ds_read_b128 v[6:9], v248 offset:36960
	global_load_dwordx4 v[154:157], v227, s[78:79] offset:1792
	s_waitcnt lgkmcnt(6)
	v_mfma_f32_32x32x16_bf16 v[82:97], v[210:213], v[14:17], v[82:97]
	ds_read_b128 v[232:235], v249 offset:41568
	s_waitcnt vmcnt(15)
	ds_write_b128 v251, v[186:189] offset:18432
	v_mfma_f32_32x32x16_bf16 v[98:113], v[214:217], v[14:17], v[98:113]
	ds_read_b128 v[10:13], v248 offset:41568
	s_waitcnt lgkmcnt(8)
	v_mfma_f32_32x32x16_bf16 v[50:65], v[210:213], v[236:239], v[50:65]
	ds_read_b128 v[14:17], v248 offset:46176
	global_load_dwordx4 v[186:189], v227, s[86:87] offset:1792
	v_mfma_f32_32x32x16_bf16 v[66:81], v[214:217], v[236:239], v[66:81]
	s_waitcnt vmcnt(15)
	ds_write_b128 v250, v[158:161] offset:27648
	s_waitcnt lgkmcnt(8)
	v_mfma_f32_32x32x16_bf16 v[18:33], v[210:213], v[2:5], v[18:33]
	ds_read_b128 v[236:239], v248 offset:50784
	v_mfma_f32_32x32x16_bf16 v[34:49], v[214:217], v[2:5], v[34:49]
	global_load_dwordx4 v[158:161], v227, s[80:81] offset:1792
	s_waitcnt lgkmcnt(6)
	v_mfma_f32_32x32x16_bf16 v[114:129], v[228:231], v[6:9], v[114:129]
	s_waitcnt vmcnt(15)
	ds_write_b128 v251, v[190:193] offset:27648
	s_waitcnt lgkmcnt(6)
	v_mfma_f32_32x32x16_bf16 v[130:145], v[232:235], v[6:9], v[130:145]
	s_waitcnt lgkmcnt(4)
	v_mfma_f32_32x32x16_bf16 v[82:97], v[228:231], v[10:13], v[82:97]
	global_load_dwordx4 v[190:193], v227, s[92:93] offset:1792
	v_mfma_f32_32x32x16_bf16 v[98:113], v[232:235], v[10:13], v[98:113]
	s_waitcnt lgkmcnt(3)
	v_mfma_f32_32x32x16_bf16 v[50:65], v[228:231], v[14:17], v[50:65]
	v_mfma_f32_32x32x16_bf16 v[66:81], v[232:235], v[14:17], v[66:81]
	s_waitcnt lgkmcnt(1)
	v_mfma_f32_32x32x16_bf16 v[18:33], v[228:231], v[236:239], v[18:33]
	v_mfma_f32_32x32x16_bf16 v[34:49], v[232:235], v[236:239], v[34:49]
	s_waitcnt lgkmcnt(0)
	s_barrier
;     ...
;   for (int kt = 0; kt < nk; ++kt) {
;     __syncthreads();
;     if (kt + 1 < nk) {
;       u16* aw = As0 + ((kt + 1) & 1) * 256 * LD;
;       u16* bw = Bs0 + ((kt + 1) & 1) * 256 * LD;
; #pragma unroll
;       for (int i = 0; i < 4; ++i) { *(u32x4*)(aw + (srow + 64 * i) * LD + skc * 8) = ra[i]; *(u32x4*)(bw + (srow + 64 * i) * LD + skc * 8) = rb[i]; }
;     }
;     if (kt + 2 < nk) {
; #pragma unroll
;       for (int i = 0; i < 4; ++i) { ra[i] = *(const u32x4*)(Ag + (size_t)(64 * i) * K + (kt + 2) * 64); rb[i] = *(const u32x4*)(Bg[i] + (kt + 2) * 64); }
;     }
;     __builtin_amdgcn_sched_barrier(0);
;     const u16* as = As0 + (kt & 1) * 256 * LD + (wr * 128 + l31) * LD + h * 8;
;     const u16* bs = Bs0 + (kt & 1) * 256 * LD + (wc * 64 + l31) * LD + h * 8;
;     if (domma)
; #pragma unroll
;     for (int ks = 0; ks < 4; ++ks) {
;       bf16x8 wf[2], xf[4];
; #pragma unroll
;       for (int ct = 0; ct < 2; ++ct) wf[ct] = *(const bf16x8*)(bs + ct * 32 * LD + ks * 16);
; #pragma unroll
;       for (int tt = 0; tt < 4; ++tt) xf[tt] = *(const bf16x8*)(as + tt * 32 * LD + ks * 16);
; #pragma unroll
;       for (int ct = 0; ct < 2; ++ct)
; #pragma unroll
;         for (int tt = 0; tt < 4; ++tt) acc[ct][tt] = __builtin_amdgcn_mfma_f32_32x32x16_bf16(wf[ct], xf[tt], acc[ct][tt], 0, 0, 0);
;     }
	ds_read_b128 v[210:213], v249
	ds_read_b128 v[236:239], v248
	ds_read_b128 v[214:217], v249 offset:4608
	ds_read_b128 v[2:5], v248 offset:4608
	ds_read_b128 v[6:9], v248 offset:9216
	ds_read_b128 v[10:13], v248 offset:13824
	s_waitcnt lgkmcnt(4)
	v_mfma_f32_32x32x16_bf16 v[114:129], v[210:213], v[236:239], v[114:129]
	ds_read_b128 v[228:231], v249 offset:32
	s_waitcnt lgkmcnt(4)
	v_mfma_f32_32x32x16_bf16 v[130:145], v[214:217], v[236:239], v[130:145]
	ds_read_b128 v[14:17], v248 offset:32
	s_waitcnt lgkmcnt(4)
	v_mfma_f32_32x32x16_bf16 v[82:97], v[210:213], v[2:5], v[82:97]
	ds_read_b128 v[232:235], v249 offset:4640
	v_mfma_f32_32x32x16_bf16 v[98:113], v[214:217], v[2:5], v[98:113]
	ds_read_b128 v[236:239], v248 offset:4640
	s_waitcnt vmcnt(15)
	ds_write_b128 v250, v[162:165] offset:36864
	s_waitcnt lgkmcnt(6)
	v_mfma_f32_32x32x16_bf16 v[50:65], v[210:213], v[6:9], v[50:65]
	ds_read_b128 v[2:5], v248 offset:9248
	v_mfma_f32_32x32x16_bf16 v[66:81], v[214:217], v[6:9], v[66:81]
	global_load_dwordx4 v[162:165], v227, s[74:75] offset:1920
	s_waitcnt lgkmcnt(6)
	v_mfma_f32_32x32x16_bf16 v[18:33], v[210:213], v[10:13], v[18:33]
	ds_read_b128 v[6:9], v248 offset:13856
	s_waitcnt vmcnt(15)
	ds_write_b128 v251, v[194:197] offset:36864
	v_mfma_f32_32x32x16_bf16 v[34:49], v[214:217], v[10:13], v[34:49]
	s_waitcnt lgkmcnt(6)
	v_mfma_f32_32x32x16_bf16 v[114:129], v[228:231], v[14:17], v[114:129]
	ds_read_b128 v[210:213], v249 offset:64
	global_load_dwordx4 v[194:197], v227, s[82:83] offset:1920
	s_waitcnt lgkmcnt(6)
	v_mfma_f32_32x32x16_bf16 v[130:145], v[232:235], v[14:17], v[130:145]
	ds_read_b128 v[10:13], v248 offset:64
	s_waitcnt vmcnt(15)
	ds_write_b128 v250, v[166:169] offset:46080
	s_waitcnt lgkmcnt(7)
	v_mfma_f32_32x32x16_bf16 v[82:97], v[228:231], v[236:239], v[82:97]
	ds_read_b128 v[214:217], v249 offset:4672
	v_mfma_f32_32x32x16_bf16 v[98:113], v[232:235], v[236:239], v[98:113]
	ds_read_b128 v[14:17], v248 offset:4672
	global_load_dwordx4 v[166:169], v227, s[76:77] offset:1920
	s_waitcnt lgkmcnt(7)
	v_mfma_f32_32x32x16_bf16 v[50:65], v[228:231], v[2:5], v[50:65]
	ds_read_b128 v[236:239], v248 offset:9280
	s_waitcnt vmcnt(15)
	ds_write_b128 v251, v[198:201] offset:46080
	v_mfma_f32_32x32x16_bf16 v[66:81], v[232:235], v[2:5], v[66:81]
	s_waitcnt lgkmcnt(8)
	v_mfma_f32_32x32x16_bf16 v[18:33], v[228:231], v[6:9], v[18:33]
	ds_read_b128 v[2:5], v248 offset:13888
	global_load_dwordx4 v[198:201], v227, s[84:85] offset:1920
	v_mfma_f32_32x32x16_bf16 v[34:49], v[232:235], v[6:9], v[34:49]
	s_waitcnt vmcnt(15)
	ds_write_b128 v250, v[170:173] offset:55296
	s_waitcnt lgkmcnt(7)
	v_mfma_f32_32x32x16_bf16 v[114:129], v[210:213], v[10:13], v[114:129]
	ds_read_b128 v[228:231], v249 offset:96
	s_waitcnt lgkmcnt(6)
	v_mfma_f32_32x32x16_bf16 v[130:145], v[214:217], v[10:13], v[130:145]
	ds_read_b128 v[6:9], v248 offset:96
	global_load_dwordx4 v[170:173], v227, s[78:79] offset:1920
	s_waitcnt lgkmcnt(6)
	v_mfma_f32_32x32x16_bf16 v[82:97], v[210:213], v[14:17], v[82:97]
	ds_read_b128 v[232:235], v249 offset:4704
	s_waitcnt vmcnt(15)
	ds_write_b128 v251, v[202:205] offset:55296
	v_mfma_f32_32x32x16_bf16 v[98:113], v[214:217], v[14:17], v[98:113]
	ds_read_b128 v[10:13], v248 offset:4704
	s_waitcnt lgkmcnt(8)
	v_mfma_f32_32x32x16_bf16 v[50:65], v[210:213], v[236:239], v[50:65]
	ds_read_b128 v[14:17], v248 offset:9312
	global_load_dwordx4 v[202:205], v227, s[86:87] offset:1920
	v_mfma_f32_32x32x16_bf16 v[66:81], v[214:217], v[236:239], v[66:81]
	s_waitcnt vmcnt(15)
	ds_write_b128 v250, v[174:177] offset:64512
	s_waitcnt lgkmcnt(8)
	v_mfma_f32_32x32x16_bf16 v[18:33], v[210:213], v[2:5], v[18:33]
	ds_read_b128 v[236:239], v248 offset:13920
	v_mfma_f32_32x32x16_bf16 v[34:49], v[214:217], v[2:5], v[34:49]
	global_load_dwordx4 v[174:177], v227, s[80:81] offset:1920
	s_waitcnt lgkmcnt(6)
	v_mfma_f32_32x32x16_bf16 v[114:129], v[228:231], v[6:9], v[114:129]
	s_waitcnt vmcnt(15)
	ds_write_b128 v251, v[206:209] offset:64512
	s_waitcnt lgkmcnt(6)
	v_mfma_f32_32x32x16_bf16 v[130:145], v[232:235], v[6:9], v[130:145]
	s_waitcnt lgkmcnt(4)
	v_mfma_f32_32x32x16_bf16 v[82:97], v[228:231], v[10:13], v[82:97]
	global_load_dwordx4 v[206:209], v227, s[92:93] offset:1920
	v_mfma_f32_32x32x16_bf16 v[98:113], v[232:235], v[10:13], v[98:113]
	s_waitcnt lgkmcnt(3)
	v_mfma_f32_32x32x16_bf16 v[50:65], v[228:231], v[14:17], v[50:65]
	v_mfma_f32_32x32x16_bf16 v[66:81], v[232:235], v[14:17], v[66:81]
	s_waitcnt lgkmcnt(1)
	v_mfma_f32_32x32x16_bf16 v[18:33], v[228:231], v[236:239], v[18:33]
	v_mfma_f32_32x32x16_bf16 v[34:49], v[232:235], v[236:239], v[34:49]
	s_waitcnt lgkmcnt(0)
	s_barrier
;     ...
;   for (int kt = 0; kt < nk; ++kt) {
;     __syncthreads();
;     if (kt + 1 < nk) {
;       u16* aw = As0 + ((kt + 1) & 1) * 256 * LD;
;       u16* bw = Bs0 + ((kt + 1) & 1) * 256 * LD;
; #pragma unroll
;       for (int i = 0; i < 4; ++i) { *(u32x4*)(aw + (srow + 64 * i) * LD + skc * 8) = ra[i]; *(u32x4*)(bw + (srow + 64 * i) * LD + skc * 8) = rb[i]; }
;     }
;     if (kt + 2 < nk) {
; #pragma unroll
;       for (int i = 0; i < 4; ++i) { ra[i] = *(const u32x4*)(Ag + (size_t)(64 * i) * K + (kt + 2) * 64); rb[i] = *(const u32x4*)(Bg[i] + (kt + 2) * 64); }
;     }
;     __builtin_amdgcn_sched_barrier(0);
;     const u16* as = As0 + (kt & 1) * 256 * LD + (wr * 128 + l31) * LD + h * 8;
;     const u16* bs = Bs0 + (kt & 1) * 256 * LD + (wc * 64 + l31) * LD + h * 8;
;     if (domma)
; #pragma unroll
;     for (int ks = 0; ks < 4; ++ks) {
;       bf16x8 wf[2], xf[4];
; #pragma unroll
;       for (int ct = 0; ct < 2; ++ct) wf[ct] = *(const bf16x8*)(bs + ct * 32 * LD + ks * 16);
; #pragma unroll
;       for (int tt = 0; tt < 4; ++tt) xf[tt] = *(const bf16x8*)(as + tt * 32 * LD + ks * 16);
; #pragma unroll
;       for (int ct = 0; ct < 2; ++ct)
; #pragma unroll
;         for (int tt = 0; tt < 4; ++tt) acc[ct][tt] = __builtin_amdgcn_mfma_f32_32x32x16_bf16(wf[ct], xf[tt], acc[ct][tt], 0, 0, 0);
;     }
	ds_read_b128 v[210:213], v249 offset:36864
	ds_read_b128 v[236:239], v248 offset:36864
	ds_read_b128 v[214:217], v249 offset:41472
	ds_read_b128 v[2:5], v248 offset:41472
	ds_read_b128 v[6:9], v248 offset:46080
	ds_read_b128 v[10:13], v248 offset:50688
	s_waitcnt lgkmcnt(4)
	v_mfma_f32_32x32x16_bf16 v[114:129], v[210:213], v[236:239], v[114:129]
	ds_read_b128 v[228:231], v249 offset:36896
	s_waitcnt lgkmcnt(4)
	v_mfma_f32_32x32x16_bf16 v[130:145], v[214:217], v[236:239], v[130:145]
	ds_read_b128 v[14:17], v248 offset:36896
	s_waitcnt lgkmcnt(4)
	v_mfma_f32_32x32x16_bf16 v[82:97], v[210:213], v[2:5], v[82:97]
	ds_read_b128 v[232:235], v249 offset:41504
	v_mfma_f32_32x32x16_bf16 v[98:113], v[214:217], v[2:5], v[98:113]
	ds_read_b128 v[236:239], v248 offset:41504
	s_waitcnt vmcnt(15)
	ds_write_b128 v250, v[146:149]
	s_waitcnt lgkmcnt(6)
	v_mfma_f32_32x32x16_bf16 v[50:65], v[210:213], v[6:9], v[50:65]
	ds_read_b128 v[2:5], v248 offset:46112
	v_mfma_f32_32x32x16_bf16 v[66:81], v[214:217], v[6:9], v[66:81]
	s_waitcnt lgkmcnt(6)
	v_mfma_f32_32x32x16_bf16 v[18:33], v[210:213], v[10:13], v[18:33]
	ds_read_b128 v[6:9], v248 offset:50720
	s_waitcnt vmcnt(14)
	ds_write_b128 v251, v[178:181]
	v_mfma_f32_32x32x16_bf16 v[34:49], v[214:217], v[10:13], v[34:49]
	s_waitcnt lgkmcnt(6)
	v_mfma_f32_32x32x16_bf16 v[114:129], v[228:231], v[14:17], v[114:129]
	ds_read_b128 v[210:213], v249 offset:36928
	s_waitcnt lgkmcnt(6)
	v_mfma_f32_32x32x16_bf16 v[130:145], v[232:235], v[14:17], v[130:145]
	ds_read_b128 v[10:13], v248 offset:36928
	s_waitcnt vmcnt(13)
	ds_write_b128 v250, v[150:153] offset:9216
	s_waitcnt lgkmcnt(7)
	v_mfma_f32_32x32x16_bf16 v[82:97], v[228:231], v[236:239], v[82:97]
	ds_read_b128 v[214:217], v249 offset:41536
	v_mfma_f32_32x32x16_bf16 v[98:113], v[232:235], v[236:239], v[98:113]
	ds_read_b128 v[14:17], v248 offset:41536
	s_waitcnt lgkmcnt(7)
	v_mfma_f32_32x32x16_bf16 v[50:65], v[228:231], v[2:5], v[50:65]
	ds_read_b128 v[236:239], v248 offset:46144
	s_waitcnt vmcnt(12)
	ds_write_b128 v251, v[182:185] offset:9216
	v_mfma_f32_32x32x16_bf16 v[66:81], v[232:235], v[2:5], v[66:81]
	s_waitcnt lgkmcnt(8)
	v_mfma_f32_32x32x16_bf16 v[18:33], v[228:231], v[6:9], v[18:33]
	ds_read_b128 v[2:5], v248 offset:50752
	v_mfma_f32_32x32x16_bf16 v[34:49], v[232:235], v[6:9], v[34:49]
	s_waitcnt vmcnt(11)
	ds_write_b128 v250, v[154:157] offset:18432
	s_waitcnt lgkmcnt(7)
	v_mfma_f32_32x32x16_bf16 v[114:129], v[210:213], v[10:13], v[114:129]
	ds_read_b128 v[228:231], v249 offset:36960
	s_waitcnt lgkmcnt(6)
	v_mfma_f32_32x32x16_bf16 v[130:145], v[214:217], v[10:13], v[130:145]
	ds_read_b128 v[6:9], v248 offset:36960
	s_waitcnt lgkmcnt(6)
	v_mfma_f32_32x32x16_bf16 v[82:97], v[210:213], v[14:17], v[82:97]
	ds_read_b128 v[232:235], v249 offset:41568
	s_waitcnt vmcnt(10)
	ds_write_b128 v251, v[186:189] offset:18432
	v_mfma_f32_32x32x16_bf16 v[98:113], v[214:217], v[14:17], v[98:113]
	ds_read_b128 v[10:13], v248 offset:41568
	s_waitcnt lgkmcnt(8)
	v_mfma_f32_32x32x16_bf16 v[50:65], v[210:213], v[236:239], v[50:65]
	ds_read_b128 v[14:17], v248 offset:46176
	v_mfma_f32_32x32x16_bf16 v[66:81], v[214:217], v[236:239], v[66:81]
	s_waitcnt vmcnt(9)
	ds_write_b128 v250, v[158:161] offset:27648
	s_waitcnt lgkmcnt(8)
	v_mfma_f32_32x32x16_bf16 v[18:33], v[210:213], v[2:5], v[18:33]
	ds_read_b128 v[236:239], v248 offset:50784
	v_mfma_f32_32x32x16_bf16 v[34:49], v[214:217], v[2:5], v[34:49]
	s_waitcnt lgkmcnt(6)
	v_mfma_f32_32x32x16_bf16 v[114:129], v[228:231], v[6:9], v[114:129]
	s_waitcnt vmcnt(8)
	ds_write_b128 v251, v[190:193] offset:27648
	s_waitcnt lgkmcnt(6)
	v_mfma_f32_32x32x16_bf16 v[130:145], v[232:235], v[6:9], v[130:145]
	s_waitcnt lgkmcnt(4)
	v_mfma_f32_32x32x16_bf16 v[82:97], v[228:231], v[10:13], v[82:97]
	v_mfma_f32_32x32x16_bf16 v[98:113], v[232:235], v[10:13], v[98:113]
	s_waitcnt lgkmcnt(3)
	v_mfma_f32_32x32x16_bf16 v[50:65], v[228:231], v[14:17], v[50:65]
	v_mfma_f32_32x32x16_bf16 v[66:81], v[232:235], v[14:17], v[66:81]
	s_waitcnt lgkmcnt(1)
	v_mfma_f32_32x32x16_bf16 v[18:33], v[228:231], v[236:239], v[18:33]
	v_mfma_f32_32x32x16_bf16 v[34:49], v[232:235], v[236:239], v[34:49]
	s_waitcnt lgkmcnt(0)
	s_barrier
	ds_read_b128 v[210:213], v249
	ds_read_b128 v[236:239], v248
	ds_read_b128 v[214:217], v249 offset:4608
	ds_read_b128 v[2:5], v248 offset:4608
	ds_read_b128 v[6:9], v248 offset:9216
	ds_read_b128 v[10:13], v248 offset:13824
	s_waitcnt lgkmcnt(4)
	v_mfma_f32_32x32x16_bf16 v[114:129], v[210:213], v[236:239], v[114:129]
	ds_read_b128 v[228:231], v249 offset:32
	s_waitcnt lgkmcnt(4)
	v_mfma_f32_32x32x16_bf16 v[130:145], v[214:217], v[236:239], v[130:145]
	ds_read_b128 v[14:17], v248 offset:32
	s_waitcnt lgkmcnt(4)
	v_mfma_f32_32x32x16_bf16 v[82:97], v[210:213], v[2:5], v[82:97]
	ds_read_b128 v[232:235], v249 offset:4640
	v_mfma_f32_32x32x16_bf16 v[98:113], v[214:217], v[2:5], v[98:113]
	ds_read_b128 v[236:239], v248 offset:4640
	s_waitcnt vmcnt(7)
	ds_write_b128 v250, v[162:165] offset:36864
	s_waitcnt lgkmcnt(6)
	v_mfma_f32_32x32x16_bf16 v[50:65], v[210:213], v[6:9], v[50:65]
	ds_read_b128 v[2:5], v248 offset:9248
	v_mfma_f32_32x32x16_bf16 v[66:81], v[214:217], v[6:9], v[66:81]
	s_waitcnt lgkmcnt(6)
	v_mfma_f32_32x32x16_bf16 v[18:33], v[210:213], v[10:13], v[18:33]
	ds_read_b128 v[6:9], v248 offset:13856
	s_waitcnt vmcnt(6)
	ds_write_b128 v251, v[194:197] offset:36864
	v_mfma_f32_32x32x16_bf16 v[34:49], v[214:217], v[10:13], v[34:49]
	s_waitcnt lgkmcnt(6)
	v_mfma_f32_32x32x16_bf16 v[114:129], v[228:231], v[14:17], v[114:129]
	ds_read_b128 v[210:213], v249 offset:64
	s_waitcnt lgkmcnt(6)
;     ...
;   for (int kt = 0; kt < nk; ++kt) {
;     __syncthreads();
;     if (kt + 1 < nk) {
;       u16* aw = As0 + ((kt + 1) & 1) * 256 * LD;
;       u16* bw = Bs0 + ((kt + 1) & 1) * 256 * LD;
; #pragma unroll
;       for (int i = 0; i < 4; ++i) { *(u32x4*)(aw + (srow + 64 * i) * LD + skc * 8) = ra[i]; *(u32x4*)(bw + (srow + 64 * i) * LD + skc * 8) = rb[i]; }
;     }
;     if (kt + 2 < nk) {
; #pragma unroll
;       for (int i = 0; i < 4; ++i) { ra[i] = *(const u32x4*)(Ag + (size_t)(64 * i) * K + (kt + 2) * 64); rb[i] = *(const u32x4*)(Bg[i] + (kt + 2) * 64); }
;     }
;     __builtin_amdgcn_sched_barrier(0);
;     const u16* as = As0 + (kt & 1) * 256 * LD + (wr * 128 + l31) * LD + h * 8;
;     const u16* bs = Bs0 + (kt & 1) * 256 * LD + (wc * 64 + l31) * LD + h * 8;
;     if (domma)
; #pragma unroll
;     for (int ks = 0; ks < 4; ++ks) {
;       bf16x8 wf[2], xf[4];
; #pragma unroll
;       for (int ct = 0; ct < 2; ++ct) wf[ct] = *(const bf16x8*)(bs + ct * 32 * LD + ks * 16);
; #pragma unroll
;       for (int tt = 0; tt < 4; ++tt) xf[tt] = *(const bf16x8*)(as + tt * 32 * LD + ks * 16);
; #pragma unroll
;       for (int ct = 0; ct < 2; ++ct)
; #pragma unroll
;         for (int tt = 0; tt < 4; ++tt) acc[ct][tt] = __builtin_amdgcn_mfma_f32_32x32x16_bf16(wf[ct], xf[tt], acc[ct][tt], 0, 0, 0);
;     }
;     __builtin_amdgcn_sched_barrier(0);
;   }
	v_mfma_f32_32x32x16_bf16 v[130:145], v[232:235], v[14:17], v[130:145]
	ds_read_b128 v[10:13], v248 offset:64
	s_waitcnt vmcnt(5)
	ds_write_b128 v250, v[166:169] offset:46080
	s_waitcnt lgkmcnt(7)
	v_mfma_f32_32x32x16_bf16 v[82:97], v[228:231], v[236:239], v[82:97]
	ds_read_b128 v[214:217], v249 offset:4672
	v_mfma_f32_32x32x16_bf16 v[98:113], v[232:235], v[236:239], v[98:113]
	ds_read_b128 v[14:17], v248 offset:4672
	s_waitcnt lgkmcnt(7)
	v_mfma_f32_32x32x16_bf16 v[50:65], v[228:231], v[2:5], v[50:65]
	ds_read_b128 v[236:239], v248 offset:9280
	s_waitcnt vmcnt(4)
	ds_write_b128 v251, v[198:201] offset:46080
	v_mfma_f32_32x32x16_bf16 v[66:81], v[232:235], v[2:5], v[66:81]
	s_waitcnt lgkmcnt(8)
	v_mfma_f32_32x32x16_bf16 v[18:33], v[228:231], v[6:9], v[18:33]
	ds_read_b128 v[2:5], v248 offset:13888
	v_mfma_f32_32x32x16_bf16 v[34:49], v[232:235], v[6:9], v[34:49]
	s_waitcnt vmcnt(3)
	ds_write_b128 v250, v[170:173] offset:55296
	s_waitcnt lgkmcnt(7)
	v_mfma_f32_32x32x16_bf16 v[114:129], v[210:213], v[10:13], v[114:129]
	ds_read_b128 v[228:231], v249 offset:96
	s_waitcnt lgkmcnt(6)
	v_mfma_f32_32x32x16_bf16 v[130:145], v[214:217], v[10:13], v[130:145]
	ds_read_b128 v[6:9], v248 offset:96
	s_waitcnt lgkmcnt(6)
	v_mfma_f32_32x32x16_bf16 v[82:97], v[210:213], v[14:17], v[82:97]
	ds_read_b128 v[232:235], v249 offset:4704
	s_waitcnt vmcnt(2)
	ds_write_b128 v251, v[202:205] offset:55296
	v_mfma_f32_32x32x16_bf16 v[98:113], v[214:217], v[14:17], v[98:113]
	ds_read_b128 v[10:13], v248 offset:4704
	s_waitcnt lgkmcnt(8)
	v_mfma_f32_32x32x16_bf16 v[50:65], v[210:213], v[236:239], v[50:65]
	ds_read_b128 v[14:17], v248 offset:9312
	v_mfma_f32_32x32x16_bf16 v[66:81], v[214:217], v[236:239], v[66:81]
	s_waitcnt vmcnt(1)
	ds_write_b128 v250, v[174:177] offset:64512
	s_waitcnt lgkmcnt(8)
	v_mfma_f32_32x32x16_bf16 v[18:33], v[210:213], v[2:5], v[18:33]
	ds_read_b128 v[236:239], v248 offset:13920
	v_mfma_f32_32x32x16_bf16 v[34:49], v[214:217], v[2:5], v[34:49]
	s_waitcnt lgkmcnt(6)
	v_mfma_f32_32x32x16_bf16 v[114:129], v[228:231], v[6:9], v[114:129]
	s_waitcnt vmcnt(0)
	ds_write_b128 v251, v[206:209] offset:64512
	s_waitcnt lgkmcnt(6)
	v_mfma_f32_32x32x16_bf16 v[130:145], v[232:235], v[6:9], v[130:145]
	s_waitcnt lgkmcnt(4)
	v_mfma_f32_32x32x16_bf16 v[82:97], v[228:231], v[10:13], v[82:97]
	v_mfma_f32_32x32x16_bf16 v[98:113], v[232:235], v[10:13], v[98:113]
	s_waitcnt lgkmcnt(3)
	v_mfma_f32_32x32x16_bf16 v[50:65], v[228:231], v[14:17], v[50:65]
	v_mfma_f32_32x32x16_bf16 v[66:81], v[232:235], v[14:17], v[66:81]
	s_waitcnt lgkmcnt(1)
	v_mfma_f32_32x32x16_bf16 v[18:33], v[228:231], v[236:239], v[18:33]
	v_mfma_f32_32x32x16_bf16 v[34:49], v[232:235], v[236:239], v[34:49]
	s_waitcnt lgkmcnt(0)
	s_barrier
	ds_read_b128 v[210:213], v249 offset:36864
	ds_read_b128 v[236:239], v248 offset:36864
	ds_read_b128 v[214:217], v249 offset:41472
	ds_read_b128 v[2:5], v248 offset:41472
	ds_read_b128 v[6:9], v248 offset:46080
	ds_read_b128 v[10:13], v248 offset:50688
	s_waitcnt lgkmcnt(4)
	v_mfma_f32_32x32x16_bf16 v[114:129], v[210:213], v[236:239], v[114:129]
	ds_read_b128 v[228:231], v249 offset:36896
	s_waitcnt lgkmcnt(4)
	v_mfma_f32_32x32x16_bf16 v[130:145], v[214:217], v[236:239], v[130:145]
	ds_read_b128 v[14:17], v248 offset:36896
	s_waitcnt lgkmcnt(4)
	v_mfma_f32_32x32x16_bf16 v[82:97], v[210:213], v[2:5], v[82:97]
	ds_read_b128 v[232:235], v249 offset:41504
	v_mfma_f32_32x32x16_bf16 v[98:113], v[214:217], v[2:5], v[98:113]
	ds_read_b128 v[236:239], v248 offset:41504
	s_waitcnt lgkmcnt(5)
	v_mfma_f32_32x32x16_bf16 v[50:65], v[210:213], v[6:9], v[50:65]
	ds_read_b128 v[2:5], v248 offset:46112
	v_mfma_f32_32x32x16_bf16 v[66:81], v[214:217], v[6:9], v[66:81]
	s_waitcnt lgkmcnt(5)
	v_mfma_f32_32x32x16_bf16 v[18:33], v[210:213], v[10:13], v[18:33]
	ds_read_b128 v[6:9], v248 offset:50720
	v_mfma_f32_32x32x16_bf16 v[34:49], v[214:217], v[10:13], v[34:49]
	s_waitcnt lgkmcnt(4)
	v_mfma_f32_32x32x16_bf16 v[114:129], v[228:231], v[14:17], v[114:129]
	ds_read_b128 v[210:213], v249 offset:36928
	s_waitcnt lgkmcnt(4)
	v_mfma_f32_32x32x16_bf16 v[130:145], v[232:235], v[14:17], v[130:145]
	ds_read_b128 v[10:13], v248 offset:36928
	s_waitcnt lgkmcnt(4)
	v_mfma_f32_32x32x16_bf16 v[82:97], v[228:231], v[236:239], v[82:97]
	ds_read_b128 v[214:217], v249 offset:41536
	v_mfma_f32_32x32x16_bf16 v[98:113], v[232:235], v[236:239], v[98:113]
	ds_read_b128 v[14:17], v248 offset:41536
	s_waitcnt lgkmcnt(5)
	v_mfma_f32_32x32x16_bf16 v[50:65], v[228:231], v[2:5], v[50:65]
	ds_read_b128 v[236:239], v248 offset:46144
	v_mfma_f32_32x32x16_bf16 v[66:81], v[232:235], v[2:5], v[66:81]
	s_waitcnt lgkmcnt(5)
	v_mfma_f32_32x32x16_bf16 v[18:33], v[228:231], v[6:9], v[18:33]
	ds_read_b128 v[2:5], v248 offset:50752
	v_mfma_f32_32x32x16_bf16 v[34:49], v[232:235], v[6:9], v[34:49]
	s_waitcnt lgkmcnt(4)
	v_mfma_f32_32x32x16_bf16 v[114:129], v[210:213], v[10:13], v[114:129]
	ds_read_b128 v[228:231], v249 offset:36960
	s_waitcnt lgkmcnt(4)
	v_mfma_f32_32x32x16_bf16 v[130:145], v[214:217], v[10:13], v[130:145]
	ds_read_b128 v[6:9], v248 offset:36960
	s_waitcnt lgkmcnt(4)
	v_mfma_f32_32x32x16_bf16 v[82:97], v[210:213], v[14:17], v[82:97]
	ds_read_b128 v[232:235], v249 offset:41568
	v_mfma_f32_32x32x16_bf16 v[98:113], v[214:217], v[14:17], v[98:113]
	ds_read_b128 v[10:13], v248 offset:41568
	s_waitcnt lgkmcnt(5)
	v_mfma_f32_32x32x16_bf16 v[50:65], v[210:213], v[236:239], v[50:65]
	ds_read_b128 v[14:17], v248 offset:46176
	v_mfma_f32_32x32x16_bf16 v[66:81], v[214:217], v[236:239], v[66:81]
	s_waitcnt lgkmcnt(5)
	v_mfma_f32_32x32x16_bf16 v[18:33], v[210:213], v[2:5], v[18:33]
	ds_read_b128 v[236:239], v248 offset:50784
	v_mfma_f32_32x32x16_bf16 v[34:49], v[214:217], v[2:5], v[34:49]
	s_waitcnt lgkmcnt(4)
	v_mfma_f32_32x32x16_bf16 v[114:129], v[228:231], v[6:9], v[114:129]
	s_waitcnt lgkmcnt(3)
	v_mfma_f32_32x32x16_bf16 v[130:145], v[232:235], v[6:9], v[130:145]
	s_waitcnt lgkmcnt(2)
	v_mfma_f32_32x32x16_bf16 v[82:97], v[228:231], v[10:13], v[82:97]
	v_mfma_f32_32x32x16_bf16 v[98:113], v[232:235], v[10:13], v[98:113]
	s_waitcnt lgkmcnt(1)
	v_mfma_f32_32x32x16_bf16 v[50:65], v[228:231], v[14:17], v[50:65]
	v_mfma_f32_32x32x16_bf16 v[66:81], v[232:235], v[14:17], v[66:81]
	s_waitcnt lgkmcnt(0)
	v_mfma_f32_32x32x16_bf16 v[18:33], v[228:231], v[236:239], v[18:33]
	v_mfma_f32_32x32x16_bf16 v[34:49], v[232:235], v[236:239], v[34:49]
	v_mov_b32_e32 v3, 0
	v_mov_b32_e32 v227, v223
	s_branch .LBB0_139
;     ...
;   for (int kt = 0; kt < nk; ++kt) {
;     __syncthreads();
;     if (kt + 1 < nk) {
;       u16* aw = As0 + ((kt + 1) & 1) * 256 * LD;
;       u16* bw = Bs0 + ((kt + 1) & 1) * 256 * LD;
; #pragma unroll
;       for (int i = 0; i < 4; ++i) { *(u32x4*)(aw + (srow + 64 * i) * LD + skc * 8) = ra[i]; *(u32x4*)(bw + (srow + 64 * i) * LD + skc * 8) = rb[i]; }
;     }
;     if (kt + 2 < nk) {
; #pragma unroll
;       for (int i = 0; i < 4; ++i) { ra[i] = *(const u32x4*)(Ag + (size_t)(64 * i) * K + (kt + 2) * 64); rb[i] = *(const u32x4*)(Bg[i] + (kt + 2) * 64); }
;     }
.Lp1_stage_only:
	v_lshrrev_b32_e32 v227, 3, v223
	v_lshlrev_b32_e32 v227, 11, v227
	v_lshlrev_b32_e32 v2, 4, v223
	v_and_b32_e32 v2, 0x70, v2
	v_or_b32_e32 v227, v227, v2
	s_lshl_b32 s6, s35, 11
	s_add_u32 s74, s16, s6
	s_addc_u32 s75, s17, 0
	s_add_u32 s76, s74, 0x20000
	s_addc_u32 s77, s75, 0
	s_add_u32 s78, s74, 0x40000
	s_addc_u32 s79, s75, 0
	s_add_u32 s80, s74, 0x60000
	s_addc_u32 s81, s75, 0
	s_lshl_b32 s6, s59, 11
	s_add_u32 s82, s18, s6
	s_addc_u32 s83, s19, 0
	s_add_u32 s84, s82, 0x20000
	s_addc_u32 s85, s83, 0
	s_add_u32 s86, s82, 0x40000
	s_addc_u32 s87, s83, 0
	s_add_u32 s92, s82, 0x60000
	s_addc_u32 s93, s83, 0
	global_load_dwordx4 v[146:149], v227, s[74:75] offset:256
	global_load_dwordx4 v[178:181], v227, s[82:83] offset:256
	global_load_dwordx4 v[150:153], v227, s[76:77] offset:256
	global_load_dwordx4 v[182:185], v227, s[84:85] offset:256
	global_load_dwordx4 v[154:157], v227, s[78:79] offset:256
	global_load_dwordx4 v[186:189], v227, s[86:87] offset:256
	global_load_dwordx4 v[158:161], v227, s[80:81] offset:256
	global_load_dwordx4 v[190:193], v227, s[92:93] offset:256
	global_load_dwordx4 v[162:165], v227, s[74:75] offset:384
	global_load_dwordx4 v[194:197], v227, s[82:83] offset:384
	global_load_dwordx4 v[166:169], v227, s[76:77] offset:384
	global_load_dwordx4 v[198:201], v227, s[84:85] offset:384
	global_load_dwordx4 v[170:173], v227, s[78:79] offset:384
	global_load_dwordx4 v[202:205], v227, s[86:87] offset:384
	global_load_dwordx4 v[174:177], v227, s[80:81] offset:384
	global_load_dwordx4 v[206:209], v227, s[92:93] offset:384
	s_waitcnt vmcnt(23)
	ds_write_b128 v251, v[36:39] offset:36864
	s_waitcnt vmcnt(22)
	ds_write_b128 v251, v[40:43] offset:46080
	s_waitcnt vmcnt(21)
	ds_write_b128 v251, v[44:47] offset:55296
	s_waitcnt vmcnt(20)
	ds_write_b128 v251, v[48:51] offset:64512
	s_waitcnt vmcnt(19)
	ds_write_b128 v250, v[52:55] offset:36864
	s_waitcnt vmcnt(18)
	ds_write_b128 v250, v[56:59] offset:46080
	s_waitcnt vmcnt(17)
	ds_write_b128 v250, v[60:63] offset:55296
	s_waitcnt vmcnt(16)
	ds_write_b128 v250, v[64:67] offset:64512
	s_waitcnt lgkmcnt(0)
	s_barrier
	s_waitcnt vmcnt(15)
	ds_write_b128 v250, v[146:149]
	global_load_dwordx4 v[146:149], v227, s[74:75] offset:512
	s_waitcnt vmcnt(15)
	ds_write_b128 v251, v[178:181]
	global_load_dwordx4 v[178:181], v227, s[82:83] offset:512
	s_waitcnt vmcnt(15)
	ds_write_b128 v250, v[150:153] offset:9216
	global_load_dwordx4 v[150:153], v227, s[76:77] offset:512
	s_waitcnt vmcnt(15)
	ds_write_b128 v251, v[182:185] offset:9216
	global_load_dwordx4 v[182:185], v227, s[84:85] offset:512
	s_waitcnt vmcnt(15)
	ds_write_b128 v250, v[154:157] offset:18432
	global_load_dwordx4 v[154:157], v227, s[78:79] offset:512
	s_waitcnt vmcnt(15)
	ds_write_b128 v251, v[186:189] offset:18432
	global_load_dwordx4 v[186:189], v227, s[86:87] offset:512
	s_waitcnt vmcnt(15)
	ds_write_b128 v250, v[158:161] offset:27648
	global_load_dwordx4 v[158:161], v227, s[80:81] offset:512
	s_waitcnt vmcnt(15)
	ds_write_b128 v251, v[190:193] offset:27648
	global_load_dwordx4 v[190:193], v227, s[92:93] offset:512
	s_waitcnt lgkmcnt(0)
	s_barrier
	s_waitcnt vmcnt(15)
	ds_write_b128 v250, v[162:165] offset:36864
	global_load_dwordx4 v[162:165], v227, s[74:75] offset:640
	s_waitcnt vmcnt(15)
	ds_write_b128 v251, v[194:197] offset:36864
	global_load_dwordx4 v[194:197], v227, s[82:83] offset:640
	s_waitcnt vmcnt(15)
	ds_write_b128 v250, v[166:169] offset:46080
	global_load_dwordx4 v[166:169], v227, s[76:77] offset:640
	s_waitcnt vmcnt(15)
	ds_write_b128 v251, v[198:201] offset:46080
	global_load_dwordx4 v[198:201], v227, s[84:85] offset:640
	s_waitcnt vmcnt(15)
	ds_write_b128 v250, v[170:173] offset:55296
	global_load_dwordx4 v[170:173], v227, s[78:79] offset:640
	s_waitcnt vmcnt(15)
	ds_write_b128 v251, v[202:205] offset:55296
	global_load_dwordx4 v[202:205], v227, s[86:87] offset:640
	s_waitcnt vmcnt(15)
	ds_write_b128 v250, v[174:177] offset:64512
	global_load_dwordx4 v[174:177], v227, s[80:81] offset:640
	s_waitcnt vmcnt(15)
	ds_write_b128 v251, v[206:209] offset:64512
	global_load_dwordx4 v[206:209], v227, s[92:93] offset:640
	s_waitcnt lgkmcnt(0)
	s_barrier
	s_waitcnt vmcnt(15)
	ds_write_b128 v250, v[146:149]
	global_load_dwordx4 v[146:149], v227, s[74:75] offset:768
	s_waitcnt vmcnt(15)
	ds_write_b128 v251, v[178:181]
	global_load_dwordx4 v[178:181], v227, s[82:83] offset:768
	s_waitcnt vmcnt(15)
	ds_write_b128 v250, v[150:153] offset:9216
	global_load_dwordx4 v[150:153], v227, s[76:77] offset:768
	s_waitcnt vmcnt(15)
	ds_write_b128 v251, v[182:185] offset:9216
	global_load_dwordx4 v[182:185], v227, s[84:85] offset:768
	s_waitcnt vmcnt(15)
	ds_write_b128 v250, v[154:157] offset:18432
	global_load_dwordx4 v[154:157], v227, s[78:79] offset:768
	s_waitcnt vmcnt(15)
	ds_write_b128 v251, v[186:189] offset:18432
	global_load_dwordx4 v[186:189], v227, s[86:87] offset:768
	s_waitcnt vmcnt(15)
	ds_write_b128 v250, v[158:161] offset:27648
	global_load_dwordx4 v[158:161], v227, s[80:81] offset:768
	s_waitcnt vmcnt(15)
	ds_write_b128 v251, v[190:193] offset:27648
	global_load_dwordx4 v[190:193], v227, s[92:93] offset:768
	s_waitcnt lgkmcnt(0)
	s_barrier
;     ...
;   for (int kt = 0; kt < nk; ++kt) {
;     __syncthreads();
;     if (kt + 1 < nk) {
;       u16* aw = As0 + ((kt + 1) & 1) * 256 * LD;
;       u16* bw = Bs0 + ((kt + 1) & 1) * 256 * LD;
; #pragma unroll
;       for (int i = 0; i < 4; ++i) { *(u32x4*)(aw + (srow + 64 * i) * LD + skc * 8) = ra[i]; *(u32x4*)(bw + (srow + 64 * i) * LD + skc * 8) = rb[i]; }
;     }
;     if (kt + 2 < nk) {
; #pragma unroll
;       for (int i = 0; i < 4; ++i) { ra[i] = *(const u32x4*)(Ag + (size_t)(64 * i) * K + (kt + 2) * 64); rb[i] = *(const u32x4*)(Bg[i] + (kt + 2) * 64); }
;     }
	s_waitcnt vmcnt(15)
	ds_write_b128 v250, v[162:165] offset:36864
	global_load_dwordx4 v[162:165], v227, s[74:75] offset:896
	s_waitcnt vmcnt(15)
	ds_write_b128 v251, v[194:197] offset:36864
	global_load_dwordx4 v[194:197], v227, s[82:83] offset:896
	s_waitcnt vmcnt(15)
	ds_write_b128 v250, v[166:169] offset:46080
	global_load_dwordx4 v[166:169], v227, s[76:77] offset:896
	s_waitcnt vmcnt(15)
	ds_write_b128 v251, v[198:201] offset:46080
	global_load_dwordx4 v[198:201], v227, s[84:85] offset:896
	s_waitcnt vmcnt(15)
	ds_write_b128 v250, v[170:173] offset:55296
	global_load_dwordx4 v[170:173], v227, s[78:79] offset:896
	s_waitcnt vmcnt(15)
	ds_write_b128 v251, v[202:205] offset:55296
	global_load_dwordx4 v[202:205], v227, s[86:87] offset:896
	s_waitcnt vmcnt(15)
	ds_write_b128 v250, v[174:177] offset:64512
	global_load_dwordx4 v[174:177], v227, s[80:81] offset:896
	s_waitcnt vmcnt(15)
	ds_write_b128 v251, v[206:209] offset:64512
	global_load_dwordx4 v[206:209], v227, s[92:93] offset:896
	s_waitcnt lgkmcnt(0)
	s_barrier
	s_waitcnt vmcnt(15)
	ds_write_b128 v250, v[146:149]
	global_load_dwordx4 v[146:149], v227, s[74:75] offset:1024
	s_waitcnt vmcnt(15)
	ds_write_b128 v251, v[178:181]
	global_load_dwordx4 v[178:181], v227, s[82:83] offset:1024
	s_waitcnt vmcnt(15)
	ds_write_b128 v250, v[150:153] offset:9216
	global_load_dwordx4 v[150:153], v227, s[76:77] offset:1024
	s_waitcnt vmcnt(15)
	ds_write_b128 v251, v[182:185] offset:9216
	global_load_dwordx4 v[182:185], v227, s[84:85] offset:1024
	s_waitcnt vmcnt(15)
	ds_write_b128 v250, v[154:157] offset:18432
	global_load_dwordx4 v[154:157], v227, s[78:79] offset:1024
	s_waitcnt vmcnt(15)
	ds_write_b128 v251, v[186:189] offset:18432
	global_load_dwordx4 v[186:189], v227, s[86:87] offset:1024
	s_waitcnt vmcnt(15)
	ds_write_b128 v250, v[158:161] offset:27648
	global_load_dwordx4 v[158:161], v227, s[80:81] offset:1024
	s_waitcnt vmcnt(15)
	ds_write_b128 v251, v[190:193] offset:27648
	global_load_dwordx4 v[190:193], v227, s[92:93] offset:1024
	s_waitcnt lgkmcnt(0)
	s_barrier
	s_waitcnt vmcnt(15)
	ds_write_b128 v250, v[162:165] offset:36864
	global_load_dwordx4 v[162:165], v227, s[74:75] offset:1152
	s_waitcnt vmcnt(15)
	ds_write_b128 v251, v[194:197] offset:36864
	global_load_dwordx4 v[194:197], v227, s[82:83] offset:1152
	s_waitcnt vmcnt(15)
	ds_write_b128 v250, v[166:169] offset:46080
	global_load_dwordx4 v[166:169], v227, s[76:77] offset:1152
	s_waitcnt vmcnt(15)
	ds_write_b128 v251, v[198:201] offset:46080
	global_load_dwordx4 v[198:201], v227, s[84:85] offset:1152
	s_waitcnt vmcnt(15)
	ds_write_b128 v250, v[170:173] offset:55296
	global_load_dwordx4 v[170:173], v227, s[78:79] offset:1152
	s_waitcnt vmcnt(15)
	ds_write_b128 v251, v[202:205] offset:55296
	global_load_dwordx4 v[202:205], v227, s[86:87] offset:1152
	s_waitcnt vmcnt(15)
	ds_write_b128 v250, v[174:177] offset:64512
	global_load_dwordx4 v[174:177], v227, s[80:81] offset:1152
	s_waitcnt vmcnt(15)
	ds_write_b128 v251, v[206:209] offset:64512
	global_load_dwordx4 v[206:209], v227, s[92:93] offset:1152
	s_waitcnt lgkmcnt(0)
	s_barrier
	s_waitcnt vmcnt(15)
	ds_write_b128 v250, v[146:149]
	global_load_dwordx4 v[146:149], v227, s[74:75] offset:1280
	s_waitcnt vmcnt(15)
	ds_write_b128 v251, v[178:181]
	global_load_dwordx4 v[178:181], v227, s[82:83] offset:1280
	s_waitcnt vmcnt(15)
	ds_write_b128 v250, v[150:153] offset:9216
	global_load_dwordx4 v[150:153], v227, s[76:77] offset:1280
	s_waitcnt vmcnt(15)
	ds_write_b128 v251, v[182:185] offset:9216
	global_load_dwordx4 v[182:185], v227, s[84:85] offset:1280
	s_waitcnt vmcnt(15)
	ds_write_b128 v250, v[154:157] offset:18432
	global_load_dwordx4 v[154:157], v227, s[78:79] offset:1280
	s_waitcnt vmcnt(15)
	ds_write_b128 v251, v[186:189] offset:18432
	global_load_dwordx4 v[186:189], v227, s[86:87] offset:1280
	s_waitcnt vmcnt(15)
	ds_write_b128 v250, v[158:161] offset:27648
	global_load_dwordx4 v[158:161], v227, s[80:81] offset:1280
	s_waitcnt vmcnt(15)
	ds_write_b128 v251, v[190:193] offset:27648
	global_load_dwordx4 v[190:193], v227, s[92:93] offset:1280
	s_waitcnt lgkmcnt(0)
	s_barrier
	s_waitcnt vmcnt(15)
	ds_write_b128 v250, v[162:165] offset:36864
	global_load_dwordx4 v[162:165], v227, s[74:75] offset:1408
	s_waitcnt vmcnt(15)
	ds_write_b128 v251, v[194:197] offset:36864
	global_load_dwordx4 v[194:197], v227, s[82:83] offset:1408
	s_waitcnt vmcnt(15)
	ds_write_b128 v250, v[166:169] offset:46080
	global_load_dwordx4 v[166:169], v227, s[76:77] offset:1408
	s_waitcnt vmcnt(15)
	ds_write_b128 v251, v[198:201] offset:46080
	global_load_dwordx4 v[198:201], v227, s[84:85] offset:1408
	s_waitcnt vmcnt(15)
	ds_write_b128 v250, v[170:173] offset:55296
	global_load_dwordx4 v[170:173], v227, s[78:79] offset:1408
	s_waitcnt vmcnt(15)
	ds_write_b128 v251, v[202:205] offset:55296
	global_load_dwordx4 v[202:205], v227, s[86:87] offset:1408
	s_waitcnt vmcnt(15)
	ds_write_b128 v250, v[174:177] offset:64512
	global_load_dwordx4 v[174:177], v227, s[80:81] offset:1408
	s_waitcnt vmcnt(15)
	ds_write_b128 v251, v[206:209] offset:64512
	global_load_dwordx4 v[206:209], v227, s[92:93] offset:1408
	s_waitcnt lgkmcnt(0)
	s_barrier
;     ...
;   for (int kt = 0; kt < nk; ++kt) {
;     __syncthreads();
;     if (kt + 1 < nk) {
;       u16* aw = As0 + ((kt + 1) & 1) * 256 * LD;
;       u16* bw = Bs0 + ((kt + 1) & 1) * 256 * LD;
; #pragma unroll
;       for (int i = 0; i < 4; ++i) { *(u32x4*)(aw + (srow + 64 * i) * LD + skc * 8) = ra[i]; *(u32x4*)(bw + (srow + 64 * i) * LD + skc * 8) = rb[i]; }
;     }
;     if (kt + 2 < nk) {
; #pragma unroll
;       for (int i = 0; i < 4; ++i) { ra[i] = *(const u32x4*)(Ag + (size_t)(64 * i) * K + (kt + 2) * 64); rb[i] = *(const u32x4*)(Bg[i] + (kt + 2) * 64); }
;     }
;     __builtin_amdgcn_sched_barrier(0);
;     const u16* as = As0 + (kt & 1) * 256 * LD + (wr * 128 + l31) * LD + h * 8;
;     const u16* bs = Bs0 + (kt & 1) * 256 * LD + (wc * 64 + l31) * LD + h * 8;
;     if (domma)
; #pragma unroll
;     for (int ks = 0; ks < 4; ++ks) {
;       bf16x8 wf[2], xf[4];
; #pragma unroll
;       for (int ct = 0; ct < 2; ++ct) wf[ct] = *(const bf16x8*)(bs + ct * 32 * LD + ks * 16);
; #pragma unroll
;       for (int tt = 0; tt < 4; ++tt) xf[tt] = *(const bf16x8*)(as + tt * 32 * LD + ks * 16);
; #pragma unroll
;       for (int ct = 0; ct < 2; ++ct)
; #pragma unroll
;         for (int tt = 0; tt < 4; ++tt) acc[ct][tt] = __builtin_amdgcn_mfma_f32_32x32x16_bf16(wf[ct], xf[tt], acc[ct][tt], 0, 0, 0);
;     }
;     __builtin_amdgcn_sched_barrier(0);
;   }
;   __syncthreads();
	s_waitcnt vmcnt(15)
	ds_write_b128 v250, v[146:149]
	global_load_dwordx4 v[146:149], v227, s[74:75] offset:1536
	s_waitcnt vmcnt(15)
	ds_write_b128 v251, v[178:181]
	global_load_dwordx4 v[178:181], v227, s[82:83] offset:1536
	s_waitcnt vmcnt(15)
	ds_write_b128 v250, v[150:153] offset:9216
	global_load_dwordx4 v[150:153], v227, s[76:77] offset:1536
	s_waitcnt vmcnt(15)
	ds_write_b128 v251, v[182:185] offset:9216
	global_load_dwordx4 v[182:185], v227, s[84:85] offset:1536
	s_waitcnt vmcnt(15)
	ds_write_b128 v250, v[154:157] offset:18432
	global_load_dwordx4 v[154:157], v227, s[78:79] offset:1536
	s_waitcnt vmcnt(15)
	ds_write_b128 v251, v[186:189] offset:18432
	global_load_dwordx4 v[186:189], v227, s[86:87] offset:1536
	s_waitcnt vmcnt(15)
	ds_write_b128 v250, v[158:161] offset:27648
	global_load_dwordx4 v[158:161], v227, s[80:81] offset:1536
	s_waitcnt vmcnt(15)
	ds_write_b128 v251, v[190:193] offset:27648
	global_load_dwordx4 v[190:193], v227, s[92:93] offset:1536
	s_waitcnt lgkmcnt(0)
	s_barrier
	s_waitcnt vmcnt(15)
	ds_write_b128 v250, v[162:165] offset:36864
	global_load_dwordx4 v[162:165], v227, s[74:75] offset:1664
	s_waitcnt vmcnt(15)
	ds_write_b128 v251, v[194:197] offset:36864
	global_load_dwordx4 v[194:197], v227, s[82:83] offset:1664
	s_waitcnt vmcnt(15)
	ds_write_b128 v250, v[166:169] offset:46080
	global_load_dwordx4 v[166:169], v227, s[76:77] offset:1664
	s_waitcnt vmcnt(15)
	ds_write_b128 v251, v[198:201] offset:46080
	global_load_dwordx4 v[198:201], v227, s[84:85] offset:1664
	s_waitcnt vmcnt(15)
	ds_write_b128 v250, v[170:173] offset:55296
	global_load_dwordx4 v[170:173], v227, s[78:79] offset:1664
	s_waitcnt vmcnt(15)
	ds_write_b128 v251, v[202:205] offset:55296
	global_load_dwordx4 v[202:205], v227, s[86:87] offset:1664
	s_waitcnt vmcnt(15)
	ds_write_b128 v250, v[174:177] offset:64512
	global_load_dwordx4 v[174:177], v227, s[80:81] offset:1664
	s_waitcnt vmcnt(15)
	ds_write_b128 v251, v[206:209] offset:64512
	global_load_dwordx4 v[206:209], v227, s[92:93] offset:1664
	s_waitcnt lgkmcnt(0)
	s_barrier
	s_waitcnt vmcnt(15)
	ds_write_b128 v250, v[146:149]
	global_load_dwordx4 v[146:149], v227, s[74:75] offset:1792
	s_waitcnt vmcnt(15)
	ds_write_b128 v251, v[178:181]
	global_load_dwordx4 v[178:181], v227, s[82:83] offset:1792
	s_waitcnt vmcnt(15)
	ds_write_b128 v250, v[150:153] offset:9216
	global_load_dwordx4 v[150:153], v227, s[76:77] offset:1792
	s_waitcnt vmcnt(15)
	ds_write_b128 v251, v[182:185] offset:9216
	global_load_dwordx4 v[182:185], v227, s[84:85] offset:1792
	s_waitcnt vmcnt(15)
	ds_write_b128 v250, v[154:157] offset:18432
	global_load_dwordx4 v[154:157], v227, s[78:79] offset:1792
	s_waitcnt vmcnt(15)
	ds_write_b128 v251, v[186:189] offset:18432
	global_load_dwordx4 v[186:189], v227, s[86:87] offset:1792
	s_waitcnt vmcnt(15)
	ds_write_b128 v250, v[158:161] offset:27648
	global_load_dwordx4 v[158:161], v227, s[80:81] offset:1792
	s_waitcnt vmcnt(15)
	ds_write_b128 v251, v[190:193] offset:27648
	global_load_dwordx4 v[190:193], v227, s[92:93] offset:1792
	s_waitcnt lgkmcnt(0)
	s_barrier
	s_waitcnt vmcnt(15)
	ds_write_b128 v250, v[162:165] offset:36864
	global_load_dwordx4 v[162:165], v227, s[74:75] offset:1920
	s_waitcnt vmcnt(15)
	ds_write_b128 v251, v[194:197] offset:36864
	global_load_dwordx4 v[194:197], v227, s[82:83] offset:1920
	s_waitcnt vmcnt(15)
	ds_write_b128 v250, v[166:169] offset:46080
	global_load_dwordx4 v[166:169], v227, s[76:77] offset:1920
	s_waitcnt vmcnt(15)
	ds_write_b128 v251, v[198:201] offset:46080
	global_load_dwordx4 v[198:201], v227, s[84:85] offset:1920
	s_waitcnt vmcnt(15)
	ds_write_b128 v250, v[170:173] offset:55296
	global_load_dwordx4 v[170:173], v227, s[78:79] offset:1920
	s_waitcnt vmcnt(15)
	ds_write_b128 v251, v[202:205] offset:55296
	global_load_dwordx4 v[202:205], v227, s[86:87] offset:1920
	s_waitcnt vmcnt(15)
	ds_write_b128 v250, v[174:177] offset:64512
	global_load_dwordx4 v[174:177], v227, s[80:81] offset:1920
	s_waitcnt vmcnt(15)
	ds_write_b128 v251, v[206:209] offset:64512
	global_load_dwordx4 v[206:209], v227, s[92:93] offset:1920
	s_waitcnt lgkmcnt(0)
	s_barrier
	s_waitcnt vmcnt(15)
	ds_write_b128 v250, v[146:149]
	s_waitcnt vmcnt(14)
	ds_write_b128 v251, v[178:181]
	s_waitcnt vmcnt(13)
	ds_write_b128 v250, v[150:153] offset:9216
	s_waitcnt vmcnt(12)
	ds_write_b128 v251, v[182:185] offset:9216
	s_waitcnt vmcnt(11)
	ds_write_b128 v250, v[154:157] offset:18432
	s_waitcnt vmcnt(10)
	ds_write_b128 v251, v[186:189] offset:18432
	s_waitcnt vmcnt(9)
	ds_write_b128 v250, v[158:161] offset:27648
	s_waitcnt vmcnt(8)
	ds_write_b128 v251, v[190:193] offset:27648
	s_waitcnt lgkmcnt(0)
	s_barrier
	s_waitcnt vmcnt(7)
	ds_write_b128 v250, v[162:165] offset:36864
	s_waitcnt vmcnt(6)
	ds_write_b128 v251, v[194:197] offset:36864
	s_waitcnt vmcnt(5)
	ds_write_b128 v250, v[166:169] offset:46080
	s_waitcnt vmcnt(4)
	ds_write_b128 v251, v[198:201] offset:46080
	s_waitcnt vmcnt(3)
	ds_write_b128 v250, v[170:173] offset:55296
	s_waitcnt vmcnt(2)
	ds_write_b128 v251, v[202:205] offset:55296
	s_waitcnt vmcnt(1)
	ds_write_b128 v250, v[174:177] offset:64512
	s_waitcnt vmcnt(0)
	ds_write_b128 v251, v[206:209] offset:64512
	s_waitcnt lgkmcnt(0)
	s_barrier
	v_mov_b32_e32 v3, 0
	v_mov_b32_e32 v227, v223
	s_branch .LBB0_139
